# ssd_out unit k-loop: fragment loads of k-steps 2..7 issued right after the first 8
# speedup vs baseline: 1.0051x; 1.0051x over previous
.LBB0_1290:
	s_or_b64 exec, exec, s[4:5]
	v_readlane_b32 s2, v254, 53
	s_waitcnt lgkmcnt(0)
	s_barrier
	v_mov_b32_e32 v0, s2
	ds_read_b32 v0, v0
	s_mov_b64 s[4:5], -1
	s_waitcnt lgkmcnt(0)
	v_readfirstlane_b32 s2, v0
	s_cmpk_gt_i32 s2, 0xff
	s_cbranch_scc1 .LBB0_1285
	s_ashr_i32 s4, s2, 5
	s_and_b32 s3, s2, 31
	s_ashr_i32 s5, s4, 31
	s_lshl_b32 s2, s2, 2
	s_lshl_b32 s16, s3, 6
	s_lshl_b64 s[14:15], s[4:5], 7
	s_and_b32 s2, s2, 0x78
	s_add_u32 s3, s14, s88
	s_addc_u32 s14, s15, 0
	s_add_u32 s2, s3, s2
	s_addc_u32 s3, s14, 0
	s_lshl_b64 s[2:3], s[2:3], 14
	v_lshl_add_u64 v[4:5], v[86:87], 0, s[2:3]
	v_mov_b32_e32 v103, v96
	v_mov_b32_e32 v105, v96
	s_lshl_b64 s[4:5], s[4:5], 11
	v_lshl_add_u64 v[80:81], v[4:5], 0, v[102:103]
	v_lshl_add_u64 v[82:83], v[4:5], 0, v[104:105]
	s_or_b32 s4, s4, s16
	global_load_dwordx4 v[0:3], v[80:81], off
	global_load_dwordx4 v[4:7], v[82:83], off
	s_lshl_b64 s[14:15], s[4:5], 9
	v_lshl_add_u64 v[12:13], v[88:89], 0, s[14:15]
	v_mov_b32_e32 v107, v96
	v_mov_b32_e32 v109, v96
	v_lshl_add_u64 v[110:111], v[12:13], 0, v[106:107]
	v_lshl_add_u64 v[112:113], v[12:13], 0, v[108:109]
	global_load_dwordx4 v[8:11], v[110:111], off
	global_load_dwordx4 v[12:15], v[112:113], off
	global_load_dwordx4 v[64:67], v[80:81], off offset:32
	global_load_dwordx4 v[68:71], v[82:83], off offset:32
	global_load_dwordx4 v[72:75], v[110:111], off offset:32
	global_load_dwordx4 v[76:79], v[112:113], off offset:32
	global_load_dwordx4 v[116:119], v[80:81], off offset:64
	global_load_dwordx4 v[120:123], v[82:83], off offset:64
	global_load_dwordx4 v[132:135], v[110:111], off offset:64
	global_load_dwordx4 v[136:139], v[112:113], off offset:64
	global_load_dwordx4 v[140:143], v[80:81], off offset:96
	global_load_dwordx4 v[148:151], v[82:83], off offset:96
	global_load_dwordx4 v[152:155], v[110:111], off offset:96
	global_load_dwordx4 v[158:161], v[112:113], off offset:96
	global_load_dwordx4 v[162:165], v[80:81], off offset:128
	global_load_dwordx4 v[166:169], v[82:83], off offset:128
	global_load_dwordx4 v[170:173], v[110:111], off offset:128
	global_load_dwordx4 v[186:189], v[112:113], off offset:128
	global_load_dwordx4 v[190:193], v[80:81], off offset:160
	global_load_dwordx4 v[194:197], v[82:83], off offset:160
	global_load_dwordx4 v[198:201], v[110:111], off offset:160
	global_load_dwordx4 v[202:205], v[112:113], off offset:160
	global_load_dwordx4 v[206:209], v[80:81], off offset:192
	global_load_dwordx4 v[210:213], v[82:83], off offset:192
	global_load_dwordx4 v[214:217], v[110:111], off offset:192
	global_load_dwordx4 v[218:221], v[112:113], off offset:192
	global_load_dwordx4 v[222:225], v[80:81], off offset:224
	global_load_dwordx4 v[226:229], v[82:83], off offset:224
	global_load_dwordx4 v[230:233], v[110:111], off offset:224
	global_load_dwordx4 v[236:239], v[112:113], off offset:224
	s_waitcnt vmcnt(29)
	v_mfma_f32_32x32x16_bf16 v[48:63], v[0:3], v[8:11], 0
	v_mfma_f32_32x32x16_bf16 v[32:47], v[4:7], v[8:11], 0
	s_waitcnt vmcnt(28)
	v_mfma_f32_32x32x16_bf16 v[16:31], v[0:3], v[12:15], 0
	v_mfma_f32_32x32x16_bf16 v[0:15], v[4:7], v[12:15], 0
	s_waitcnt vmcnt(25)
	v_mfma_f32_32x32x16_bf16 v[48:63], v[64:67], v[72:75], v[48:63]
	v_mfma_f32_32x32x16_bf16 v[32:47], v[68:71], v[72:75], v[32:47]
	s_waitcnt vmcnt(24)
	v_mfma_f32_32x32x16_bf16 v[16:31], v[64:67], v[76:79], v[16:31]
	v_mfma_f32_32x32x16_bf16 v[0:15], v[68:71], v[76:79], v[0:15]
	s_waitcnt vmcnt(21)
	v_mfma_f32_32x32x16_bf16 v[48:63], v[116:119], v[132:135], v[48:63]
	v_mfma_f32_32x32x16_bf16 v[32:47], v[120:123], v[132:135], v[32:47]
	s_waitcnt vmcnt(20)
	v_mfma_f32_32x32x16_bf16 v[16:31], v[116:119], v[136:139], v[16:31]
	v_mfma_f32_32x32x16_bf16 v[0:15], v[120:123], v[136:139], v[0:15]
	s_waitcnt vmcnt(17)
	v_mfma_f32_32x32x16_bf16 v[48:63], v[140:143], v[152:155], v[48:63]
	v_mfma_f32_32x32x16_bf16 v[32:47], v[148:151], v[152:155], v[32:47]
	s_waitcnt vmcnt(16)
	v_mfma_f32_32x32x16_bf16 v[16:31], v[140:143], v[158:161], v[16:31]
	v_mfma_f32_32x32x16_bf16 v[0:15], v[148:151], v[158:161], v[0:15]
	s_waitcnt vmcnt(13)
	v_mfma_f32_32x32x16_bf16 v[48:63], v[162:165], v[170:173], v[48:63]
	v_mfma_f32_32x32x16_bf16 v[32:47], v[166:169], v[170:173], v[32:47]
	s_waitcnt vmcnt(12)
	v_mfma_f32_32x32x16_bf16 v[16:31], v[162:165], v[186:189], v[16:31]
	v_mfma_f32_32x32x16_bf16 v[0:15], v[166:169], v[186:189], v[0:15]
	s_waitcnt vmcnt(9)
	v_mfma_f32_32x32x16_bf16 v[48:63], v[190:193], v[198:201], v[48:63]
	v_mfma_f32_32x32x16_bf16 v[32:47], v[194:197], v[198:201], v[32:47]
	s_waitcnt vmcnt(8)
	v_mfma_f32_32x32x16_bf16 v[16:31], v[190:193], v[202:205], v[16:31]
	v_mfma_f32_32x32x16_bf16 v[0:15], v[194:197], v[202:205], v[0:15]
	s_waitcnt vmcnt(5)
	v_mfma_f32_32x32x16_bf16 v[48:63], v[206:209], v[214:217], v[48:63]
	v_mfma_f32_32x32x16_bf16 v[32:47], v[210:213], v[214:217], v[32:47]
	s_waitcnt vmcnt(4)
	v_mfma_f32_32x32x16_bf16 v[16:31], v[206:209], v[218:221], v[16:31]
	v_mfma_f32_32x32x16_bf16 v[0:15], v[210:213], v[218:221], v[0:15]
	s_barrier
	s_waitcnt vmcnt(1)
	v_mfma_f32_32x32x16_bf16 v[32:47], v[226:229], v[230:233], v[32:47]
	s_waitcnt vmcnt(0)
	v_mfma_f32_32x32x16_bf16 v[0:15], v[226:229], v[236:239], v[0:15]
	v_mov_b32_e32 v69, s5
	v_or_b32_e32 v68, s4, v84
	v_lshlrev_b64 v[110:111], 11, v[68:69]
	v_mad_u64_u32 v[130:131], s[2:3], v68, s42, v[98:99]
	v_lshl_add_u64 v[128:129], v[94:95], 0, v[110:111]
	v_mfma_f32_32x32x16_bf16 v[48:63], v[222:225], v[230:233], v[48:63]
	v_mfma_f32_32x32x16_bf16 v[16:31], v[222:225], v[236:239], v[16:31]
	v_lshlrev_b64 v[64:65], 5, v[68:69]
	v_lshl_add_u64 v[64:65], s[8:9], 0, v[64:65]
	global_load_dword v142, v[64:65], off
	v_mov_b32_e32 v68, 0x2800
	v_mad_i32_i24 v131, s5, v68, v131
	global_load_dwordx4 v[64:67], v[128:129], off
	global_load_dwordx4 v[112:115], v[130:131], off
	global_load_dwordx4 v[120:123], v[128:129], off offset:32
	global_load_dwordx4 v[132:135], v[130:131], off offset:32
	global_load_dwordx4 v[80:83], v[128:129], off offset:64
	global_load_dwordx4 v[76:79], v[130:131], off offset:64
	global_load_dwordx4 v[72:75], v[128:129], off offset:96
	global_load_dwordx4 v[68:71], v[130:131], off offset:96
	global_load_dwordx4 v[186:189], v[128:129], off offset:128
	global_load_dwordx4 v[190:193], v[130:131], off offset:128
	global_load_dwordx4 v[194:197], v[128:129], off offset:160
	global_load_dwordx4 v[198:201], v[130:131], off offset:160
	global_load_dwordx4 v[202:205], v[128:129], off offset:192
	global_load_dwordx4 v[206:209], v[130:131], off offset:192
	global_load_dwordx4 v[210:213], v[128:129], off offset:224
	global_load_dwordx4 v[214:217], v[130:131], off offset:224
	s_waitcnt vmcnt(16)
	v_exp_f32_e32 v124, v142
	s_waitcnt vmcnt(14)
	v_mul_f32_e32 v103, 0xbfb8aa3b, v112
	v_fma_f32 v105, v112, s43, -v103
	v_rndne_f32_e32 v107, v103
	v_fmac_f32_e32 v105, 0xb2a5705f, v112
	v_sub_f32_e32 v103, v103, v107
	v_add_f32_e32 v103, v103, v105
	v_exp_f32_e32 v103, v103
	v_cvt_i32_f32_e32 v105, v107
	v_cmp_nlt_f32_e32 vcc, s34, v112
	v_pk_fma_f32 v[48:49], v[48:49], v[124:125], v[64:65] op_sel_hi:[1,0,1]
	v_pk_fma_f32 v[50:51], v[50:51], v[124:125], v[66:67] op_sel_hi:[1,0,1]
	v_ldexp_f32 v103, v103, v105
	v_cndmask_b32_e32 v103, 0, v103, vcc
	v_cmp_ngt_f32_e32 vcc, s35, v112
	s_waitcnt vmcnt(13)
	v_pk_fma_f32 v[52:53], v[52:53], v[124:125], v[120:121] op_sel_hi:[1,0,1]
	v_cndmask_b32_e32 v116, v179, v103, vcc
	v_mul_f32_e32 v103, 0xbfb8aa3b, v113
	v_fma_f32 v105, v113, s43, -v103
	v_rndne_f32_e32 v107, v103
	v_fmac_f32_e32 v105, 0xb2a5705f, v113
	v_sub_f32_e32 v103, v103, v107
	v_add_f32_e32 v103, v103, v105
	v_exp_f32_e32 v103, v103
	v_cvt_i32_f32_e32 v105, v107
	v_cmp_nlt_f32_e32 vcc, s34, v113
	v_ldexp_f32 v103, v103, v105
	s_nop 0
	v_cndmask_b32_e32 v103, 0, v103, vcc
	v_cmp_ngt_f32_e32 vcc, s35, v113
	s_nop 1
	v_cndmask_b32_e32 v117, v179, v103, vcc
	v_pk_add_f32 v[64:65], v[116:117], 1.0 op_sel_hi:[1,0]
	s_nop 0
	v_div_scale_f32 v103, s[2:3], v65, v65, v113
	v_rcp_f32_e32 v105, v103
	s_nop 0
	v_fma_f32 v107, -v103, v105, 1.0
	v_fmac_f32_e32 v105, v107, v105
	v_div_scale_f32 v107, vcc, v113, v65, v113
	v_mul_f32_e32 v109, v107, v105
	v_fma_f32 v116, -v103, v109, v107
	v_fmac_f32_e32 v109, v116, v105
	v_fma_f32 v103, -v103, v109, v107
	v_div_fmas_f32 v103, v103, v105, v109
	v_div_fixup_f32 v65, v103, v65, v113
	v_div_scale_f32 v103, s[2:3], v64, v64, v112
	v_rcp_f32_e32 v105, v103
	s_nop 0
	v_fma_f32 v107, -v103, v105, 1.0
	v_fmac_f32_e32 v105, v107, v105
	v_div_scale_f32 v107, vcc, v112, v64, v112
	v_mul_f32_e32 v109, v107, v105
	v_fma_f32 v113, -v103, v109, v107
	v_fmac_f32_e32 v109, v113, v105
	v_fma_f32 v103, -v103, v109, v107
	v_div_fmas_f32 v103, v103, v105, v109
	v_div_fixup_f32 v64, v103, v64, v112
	v_pk_mul_f32 v[116:117], v[48:49], v[64:65]
	v_mul_f32_e32 v64, 0xbfb8aa3b, v114
	v_fma_f32 v65, v114, s43, -v64
	v_rndne_f32_e32 v103, v64
	v_fmac_f32_e32 v65, 0xb2a5705f, v114
	v_sub_f32_e32 v64, v64, v103
	v_add_f32_e32 v64, v64, v65
	v_exp_f32_e32 v64, v64
	v_cvt_i32_f32_e32 v65, v103
	v_cmp_nlt_f32_e32 vcc, s34, v114
	v_mul_f32_e32 v48, v117, v117
	v_pk_fma_f32 v[48:49], v[116:117], v[116:117], v[48:49] op_sel_hi:[1,1,0]
	v_ldexp_f32 v64, v64, v65
	v_mul_f32_e32 v65, 0xbfb8aa3b, v115
	v_fma_f32 v103, v115, s43, -v65
	v_rndne_f32_e32 v105, v65
	v_fmac_f32_e32 v103, 0xb2a5705f, v115
	v_sub_f32_e32 v65, v65, v105
	v_add_f32_e32 v65, v65, v103
	v_exp_f32_e32 v65, v65
	v_cvt_i32_f32_e32 v103, v105
	v_cndmask_b32_e32 v64, 0, v64, vcc
	v_cmp_ngt_f32_e32 vcc, s35, v114
	v_ldexp_f32 v65, v65, v103
	s_nop 0
	v_cndmask_b32_e32 v64, v179, v64, vcc
	v_cmp_nlt_f32_e32 vcc, s34, v115
	s_nop 1
	v_cndmask_b32_e32 v65, 0, v65, vcc
	v_cmp_ngt_f32_e32 vcc, s35, v115
	s_nop 1
	v_cndmask_b32_e32 v65, v179, v65, vcc
	v_pk_add_f32 v[64:65], v[64:65], 1.0 op_sel_hi:[1,0]
	s_nop 0
	v_div_scale_f32 v66, s[2:3], v65, v65, v115
	v_rcp_f32_e32 v67, v66
	s_nop 0
	v_fma_f32 v103, -v66, v67, 1.0
	v_fmac_f32_e32 v67, v103, v67
	v_div_scale_f32 v103, vcc, v115, v65, v115
	v_mul_f32_e32 v105, v103, v67
	v_fma_f32 v107, -v66, v105, v103
	v_fmac_f32_e32 v105, v107, v67
	v_fma_f32 v66, -v66, v105, v103
	v_div_fmas_f32 v66, v66, v67, v105
	v_div_fixup_f32 v65, v66, v65, v115
	v_div_scale_f32 v66, s[2:3], v64, v64, v114
	v_rcp_f32_e32 v67, v66
	s_nop 0
	v_fma_f32 v103, -v66, v67, 1.0
	v_fmac_f32_e32 v67, v103, v67
	v_div_scale_f32 v103, vcc, v114, v64, v114
	v_mul_f32_e32 v105, v103, v67
	v_fma_f32 v107, -v66, v105, v103
	v_fmac_f32_e32 v105, v107, v67
	v_fma_f32 v66, -v66, v105, v103
	v_div_fmas_f32 v66, v66, v67, v105
	v_div_fixup_f32 v64, v66, v64, v114
	v_pk_mul_f32 v[118:119], v[50:51], v[64:65]
	s_waitcnt vmcnt(12)
	v_cmp_nlt_f32_e32 vcc, s34, v132
	v_pk_fma_f32 v[48:49], v[118:119], v[118:119], v[48:49]
	v_mul_f32_e32 v50, v119, v119
	v_pk_add_f32 v[48:49], v[50:51], v[48:49] op_sel_hi:[0,1]
	v_mul_f32_e32 v50, 0xbfb8aa3b, v132
	v_fma_f32 v51, v132, s43, -v50
	v_rndne_f32_e32 v64, v50
	v_fmac_f32_e32 v51, 0xb2a5705f, v132
	v_sub_f32_e32 v50, v50, v64
	v_add_f32_e32 v50, v50, v51
	v_exp_f32_e32 v50, v50
	v_cvt_i32_f32_e32 v51, v64
	v_ldexp_f32 v50, v50, v51
	v_mul_f32_e32 v51, 0xbfb8aa3b, v133
	v_fma_f32 v64, v133, s43, -v51
	v_rndne_f32_e32 v65, v51
	v_fmac_f32_e32 v64, 0xb2a5705f, v133
	v_sub_f32_e32 v51, v51, v65
	v_add_f32_e32 v51, v51, v64
	v_exp_f32_e32 v51, v51
	v_cvt_i32_f32_e32 v64, v65
	v_cndmask_b32_e32 v50, 0, v50, vcc
	v_cmp_ngt_f32_e32 vcc, s35, v132
	v_ldexp_f32 v51, v51, v64
	s_nop 0
	v_cndmask_b32_e32 v50, v179, v50, vcc
	v_cmp_nlt_f32_e32 vcc, s34, v133
	s_nop 1
	v_cndmask_b32_e32 v51, 0, v51, vcc
	v_cmp_ngt_f32_e32 vcc, s35, v133
	s_nop 1
	v_cndmask_b32_e32 v51, v179, v51, vcc
	v_pk_add_f32 v[50:51], v[50:51], 1.0 op_sel_hi:[1,0]
	s_nop 0
	v_div_scale_f32 v64, s[2:3], v51, v51, v133
	v_rcp_f32_e32 v65, v64
	s_nop 0
	v_fma_f32 v66, -v64, v65, 1.0
	v_fmac_f32_e32 v65, v66, v65
	v_div_scale_f32 v66, vcc, v133, v51, v133
	v_mul_f32_e32 v67, v66, v65
	v_fma_f32 v103, -v64, v67, v66
	v_fmac_f32_e32 v67, v103, v65
	v_fma_f32 v64, -v64, v67, v66
	v_div_fmas_f32 v64, v64, v65, v67
	v_div_fixup_f32 v51, v64, v51, v133
	v_div_scale_f32 v64, s[2:3], v50, v50, v132
	v_rcp_f32_e32 v65, v64
	s_nop 0
	v_fma_f32 v66, -v64, v65, 1.0
	v_fmac_f32_e32 v65, v66, v65
	v_div_scale_f32 v66, vcc, v132, v50, v132
	v_mul_f32_e32 v67, v66, v65
	v_fma_f32 v103, -v64, v67, v66
	v_fmac_f32_e32 v67, v103, v65
	v_fma_f32 v64, -v64, v67, v66
	v_div_fmas_f32 v64, v64, v65, v67
	v_div_fixup_f32 v50, v64, v50, v132
	v_pk_mul_f32 v[112:113], v[52:53], v[50:51]
	v_cmp_nlt_f32_e32 vcc, s34, v134
	v_pk_fma_f32 v[48:49], v[112:113], v[112:113], v[48:49]
	v_mul_f32_e32 v50, v113, v113
	v_pk_add_f32 v[48:49], v[50:51], v[48:49] op_sel_hi:[0,1]
	v_mul_f32_e32 v50, 0xbfb8aa3b, v134
	v_fma_f32 v51, v134, s43, -v50
	v_rndne_f32_e32 v52, v50
	v_fmac_f32_e32 v51, 0xb2a5705f, v134
	v_sub_f32_e32 v50, v50, v52
	v_add_f32_e32 v50, v50, v51
	v_exp_f32_e32 v50, v50
	v_cvt_i32_f32_e32 v51, v52
	v_ldexp_f32 v50, v50, v51
	v_mul_f32_e32 v51, 0xbfb8aa3b, v135
	v_fma_f32 v52, v135, s43, -v51
	v_rndne_f32_e32 v53, v51
	v_fmac_f32_e32 v52, 0xb2a5705f, v135
	v_sub_f32_e32 v51, v51, v53
	v_add_f32_e32 v51, v51, v52
	v_exp_f32_e32 v51, v51
	v_cvt_i32_f32_e32 v52, v53
	v_cndmask_b32_e32 v50, 0, v50, vcc
	v_cmp_ngt_f32_e32 vcc, s35, v134
	v_ldexp_f32 v51, v51, v52
	s_nop 0
	v_cndmask_b32_e32 v50, v179, v50, vcc
	v_cmp_nlt_f32_e32 vcc, s34, v135
	v_pk_fma_f32 v[52:53], v[54:55], v[124:125], v[122:123] op_sel_hi:[1,0,1]
	s_nop 0
	v_cndmask_b32_e32 v51, 0, v51, vcc
	v_cmp_ngt_f32_e32 vcc, s35, v135
	s_nop 1
	v_cndmask_b32_e32 v51, v179, v51, vcc
	v_pk_add_f32 v[50:51], v[50:51], 1.0 op_sel_hi:[1,0]
	s_nop 0
	v_div_scale_f32 v54, s[2:3], v51, v51, v135
	v_rcp_f32_e32 v55, v54
	s_nop 0
	v_fma_f32 v64, -v54, v55, 1.0
	v_fmac_f32_e32 v55, v64, v55
	v_div_scale_f32 v64, vcc, v135, v51, v135
	v_mul_f32_e32 v65, v64, v55
	v_fma_f32 v66, -v54, v65, v64
	v_fmac_f32_e32 v65, v66, v55
	v_fma_f32 v54, -v54, v65, v64
	v_div_fmas_f32 v54, v54, v55, v65
	v_div_fixup_f32 v51, v54, v51, v135
	v_div_scale_f32 v54, s[2:3], v50, v50, v134
	v_rcp_f32_e32 v55, v54
	s_nop 0
	v_fma_f32 v64, -v54, v55, 1.0
	v_fmac_f32_e32 v55, v64, v55
	v_div_scale_f32 v64, vcc, v134, v50, v134
	v_mul_f32_e32 v65, v64, v55
	v_fma_f32 v66, -v54, v65, v64
	v_fmac_f32_e32 v65, v66, v55
	v_fma_f32 v54, -v54, v65, v64
	v_div_fmas_f32 v54, v54, v55, v65
	v_div_fixup_f32 v50, v54, v50, v134
	v_pk_mul_f32 v[114:115], v[52:53], v[50:51]
	s_waitcnt vmcnt(10)
	v_cmp_nlt_f32_e32 vcc, s34, v76
	v_pk_fma_f32 v[48:49], v[114:115], v[114:115], v[48:49]
	v_mul_f32_e32 v50, v115, v115
	v_pk_add_f32 v[48:49], v[50:51], v[48:49] op_sel_hi:[0,1]
	v_mul_f32_e32 v50, 0xbfb8aa3b, v76
	v_fma_f32 v51, v76, s43, -v50
	v_rndne_f32_e32 v52, v50
	v_fmac_f32_e32 v51, 0xb2a5705f, v76
	v_sub_f32_e32 v50, v50, v52
	v_add_f32_e32 v50, v50, v51
	v_exp_f32_e32 v50, v50
	v_cvt_i32_f32_e32 v51, v52
	v_ldexp_f32 v50, v50, v51
	v_mul_f32_e32 v51, 0xbfb8aa3b, v77
	v_fma_f32 v52, v77, s43, -v51
	v_rndne_f32_e32 v53, v51
	v_fmac_f32_e32 v52, 0xb2a5705f, v77
	v_sub_f32_e32 v51, v51, v53
	v_add_f32_e32 v51, v51, v52
	v_exp_f32_e32 v51, v51
	v_cvt_i32_f32_e32 v52, v53
	v_cndmask_b32_e32 v50, 0, v50, vcc
	v_cmp_ngt_f32_e32 vcc, s35, v76
	v_ldexp_f32 v51, v51, v52
	s_nop 0
	v_cndmask_b32_e32 v50, v179, v50, vcc
	v_cmp_nlt_f32_e32 vcc, s34, v77
	v_pk_fma_f32 v[52:53], v[56:57], v[124:125], v[80:81] op_sel_hi:[1,0,1]
	s_nop 0
	v_cndmask_b32_e32 v51, 0, v51, vcc
	v_cmp_ngt_f32_e32 vcc, s35, v77
	s_nop 1
	v_cndmask_b32_e32 v51, v179, v51, vcc
	v_pk_add_f32 v[50:51], v[50:51], 1.0 op_sel_hi:[1,0]
	s_nop 0
	v_div_scale_f32 v54, s[2:3], v51, v51, v77
	v_rcp_f32_e32 v55, v54
	s_nop 0
	v_fma_f32 v56, -v54, v55, 1.0
	v_fmac_f32_e32 v55, v56, v55
	v_div_scale_f32 v56, vcc, v77, v51, v77
	v_mul_f32_e32 v57, v56, v55
	v_fma_f32 v64, -v54, v57, v56
	v_fmac_f32_e32 v57, v64, v55
	v_fma_f32 v54, -v54, v57, v56
	v_div_fmas_f32 v54, v54, v55, v57
	v_div_fixup_f32 v51, v54, v51, v77
	v_div_scale_f32 v54, s[2:3], v50, v50, v76
	v_rcp_f32_e32 v55, v54
	s_nop 0
	v_fma_f32 v56, -v54, v55, 1.0
	v_fmac_f32_e32 v55, v56, v55
	v_div_scale_f32 v56, vcc, v76, v50, v76
	v_mul_f32_e32 v57, v56, v55
	v_fma_f32 v64, -v54, v57, v56
	v_fmac_f32_e32 v57, v64, v55
	v_fma_f32 v54, -v54, v57, v56
	v_div_fmas_f32 v54, v54, v55, v57
	v_div_fixup_f32 v50, v54, v50, v76
	v_pk_mul_f32 v[80:81], v[52:53], v[50:51]
	v_cmp_nlt_f32_e32 vcc, s34, v78
	v_pk_fma_f32 v[48:49], v[80:81], v[80:81], v[48:49]
	v_mul_f32_e32 v50, v81, v81
	v_pk_add_f32 v[48:49], v[50:51], v[48:49] op_sel_hi:[0,1]
	v_mul_f32_e32 v50, 0xbfb8aa3b, v78
	v_fma_f32 v51, v78, s43, -v50
	v_rndne_f32_e32 v52, v50
	v_fmac_f32_e32 v51, 0xb2a5705f, v78
	v_sub_f32_e32 v50, v50, v52
	v_add_f32_e32 v50, v50, v51
	v_exp_f32_e32 v50, v50
	v_cvt_i32_f32_e32 v51, v52
	v_ldexp_f32 v50, v50, v51
	v_mul_f32_e32 v51, 0xbfb8aa3b, v79
	v_fma_f32 v52, v79, s43, -v51
	v_rndne_f32_e32 v53, v51
	v_fmac_f32_e32 v52, 0xb2a5705f, v79
	v_sub_f32_e32 v51, v51, v53
	v_add_f32_e32 v51, v51, v52
	v_exp_f32_e32 v51, v51
	v_cvt_i32_f32_e32 v52, v53
	v_cndmask_b32_e32 v50, 0, v50, vcc
	v_cmp_ngt_f32_e32 vcc, s35, v78
	v_ldexp_f32 v51, v51, v52
	s_nop 0
	v_cndmask_b32_e32 v50, v179, v50, vcc
	v_cmp_nlt_f32_e32 vcc, s34, v79
	v_pk_fma_f32 v[52:53], v[58:59], v[124:125], v[82:83] op_sel_hi:[1,0,1]
	s_nop 0
	v_cndmask_b32_e32 v51, 0, v51, vcc
	v_cmp_ngt_f32_e32 vcc, s35, v79
	s_nop 1
	v_cndmask_b32_e32 v51, v179, v51, vcc
	v_pk_add_f32 v[50:51], v[50:51], 1.0 op_sel_hi:[1,0]
	s_nop 0
	v_div_scale_f32 v54, s[2:3], v51, v51, v79
	v_rcp_f32_e32 v55, v54
	s_nop 0
	v_fma_f32 v56, -v54, v55, 1.0
	v_fmac_f32_e32 v55, v56, v55
	v_div_scale_f32 v56, vcc, v79, v51, v79
	v_mul_f32_e32 v57, v56, v55
	v_fma_f32 v58, -v54, v57, v56
	v_fmac_f32_e32 v57, v58, v55
	v_fma_f32 v54, -v54, v57, v56
	v_div_fmas_f32 v54, v54, v55, v57
	v_div_fixup_f32 v51, v54, v51, v79
	v_div_scale_f32 v54, s[2:3], v50, v50, v78
	v_rcp_f32_e32 v55, v54
	s_nop 0
	v_fma_f32 v56, -v54, v55, 1.0
	v_fmac_f32_e32 v55, v56, v55
	v_div_scale_f32 v56, vcc, v78, v50, v78
	v_mul_f32_e32 v57, v56, v55
	v_fma_f32 v58, -v54, v57, v56
	v_fmac_f32_e32 v57, v58, v55
	v_fma_f32 v54, -v54, v57, v56
	v_div_fmas_f32 v54, v54, v55, v57
	v_div_fixup_f32 v50, v54, v50, v78
	v_pk_mul_f32 v[82:83], v[52:53], v[50:51]
	s_waitcnt vmcnt(8)
	v_cmp_nlt_f32_e32 vcc, s34, v68
	v_pk_fma_f32 v[48:49], v[82:83], v[82:83], v[48:49]
	v_mul_f32_e32 v50, v83, v83
	v_pk_add_f32 v[48:49], v[50:51], v[48:49] op_sel_hi:[0,1]
	v_mul_f32_e32 v50, 0xbfb8aa3b, v68
	v_fma_f32 v51, v68, s43, -v50
	v_rndne_f32_e32 v52, v50
	v_fmac_f32_e32 v51, 0xb2a5705f, v68
	v_sub_f32_e32 v50, v50, v52
	v_add_f32_e32 v50, v50, v51
	v_exp_f32_e32 v50, v50
	v_cvt_i32_f32_e32 v51, v52
	v_ldexp_f32 v50, v50, v51
	v_mul_f32_e32 v51, 0xbfb8aa3b, v69
	v_fma_f32 v52, v69, s43, -v51
	v_rndne_f32_e32 v53, v51
	v_fmac_f32_e32 v52, 0xb2a5705f, v69
	v_sub_f32_e32 v51, v51, v53
	v_add_f32_e32 v51, v51, v52
	v_exp_f32_e32 v51, v51
	v_cvt_i32_f32_e32 v52, v53
	v_cndmask_b32_e32 v50, 0, v50, vcc
	v_cmp_ngt_f32_e32 vcc, s35, v68
	v_ldexp_f32 v51, v51, v52
	s_nop 0
	v_cndmask_b32_e32 v50, v179, v50, vcc
	v_cmp_nlt_f32_e32 vcc, s34, v69
	v_pk_fma_f32 v[52:53], v[60:61], v[124:125], v[72:73] op_sel_hi:[1,0,1]
	s_nop 0
	v_cndmask_b32_e32 v51, 0, v51, vcc
	v_cmp_ngt_f32_e32 vcc, s35, v69
	s_nop 1
	v_cndmask_b32_e32 v51, v179, v51, vcc
	v_pk_add_f32 v[50:51], v[50:51], 1.0 op_sel_hi:[1,0]
	s_nop 0
	v_div_scale_f32 v54, s[2:3], v51, v51, v69
	v_rcp_f32_e32 v55, v54
	s_nop 0
	v_fma_f32 v56, -v54, v55, 1.0
	v_fmac_f32_e32 v55, v56, v55
	v_div_scale_f32 v56, vcc, v69, v51, v69
	v_mul_f32_e32 v57, v56, v55
	v_fma_f32 v58, -v54, v57, v56
	v_fmac_f32_e32 v57, v58, v55
	v_fma_f32 v54, -v54, v57, v56
	v_div_fmas_f32 v54, v54, v55, v57
	v_div_fixup_f32 v51, v54, v51, v69
	v_div_scale_f32 v54, s[2:3], v50, v50, v68
	v_rcp_f32_e32 v55, v54
	s_nop 0
	v_fma_f32 v56, -v54, v55, 1.0
	v_fmac_f32_e32 v55, v56, v55
	v_div_scale_f32 v56, vcc, v68, v50, v68
	v_mul_f32_e32 v57, v56, v55
	v_fma_f32 v58, -v54, v57, v56
	v_fmac_f32_e32 v57, v58, v55
	v_fma_f32 v54, -v54, v57, v56
	v_div_fmas_f32 v54, v54, v55, v57
	v_div_fixup_f32 v50, v54, v50, v68
	v_pk_mul_f32 v[120:121], v[52:53], v[50:51]
	v_cmp_nlt_f32_e32 vcc, s34, v70
	v_pk_fma_f32 v[48:49], v[120:121], v[120:121], v[48:49]
	v_mul_f32_e32 v50, v121, v121
	v_pk_add_f32 v[48:49], v[50:51], v[48:49] op_sel_hi:[0,1]
	v_mul_f32_e32 v50, 0xbfb8aa3b, v70
	v_fma_f32 v51, v70, s43, -v50
	v_rndne_f32_e32 v52, v50
	v_fmac_f32_e32 v51, 0xb2a5705f, v70
	v_sub_f32_e32 v50, v50, v52
	v_add_f32_e32 v50, v50, v51
	v_exp_f32_e32 v50, v50
	v_cvt_i32_f32_e32 v51, v52
	v_ldexp_f32 v50, v50, v51
	v_mul_f32_e32 v51, 0xbfb8aa3b, v71
	v_fma_f32 v52, v71, s43, -v51
	v_rndne_f32_e32 v53, v51
	v_fmac_f32_e32 v52, 0xb2a5705f, v71
	v_sub_f32_e32 v51, v51, v53
	v_add_f32_e32 v51, v51, v52
	v_exp_f32_e32 v51, v51
	v_cvt_i32_f32_e32 v52, v53
	v_cndmask_b32_e32 v50, 0, v50, vcc
	v_cmp_ngt_f32_e32 vcc, s35, v70
	v_ldexp_f32 v51, v51, v52
	s_nop 0
	v_cndmask_b32_e32 v50, v179, v50, vcc
	v_cmp_nlt_f32_e32 vcc, s34, v71
	v_pk_fma_f32 v[52:53], v[62:63], v[124:125], v[74:75] op_sel_hi:[1,0,1]
	s_nop 0
	v_cndmask_b32_e32 v51, 0, v51, vcc
	v_cmp_ngt_f32_e32 vcc, s35, v71
	s_nop 1
	v_cndmask_b32_e32 v51, v179, v51, vcc
	v_pk_add_f32 v[50:51], v[50:51], 1.0 op_sel_hi:[1,0]
	s_nop 0
	v_div_scale_f32 v54, s[2:3], v51, v51, v71
	v_rcp_f32_e32 v55, v54
	s_nop 0
	v_fma_f32 v56, -v54, v55, 1.0
	v_fmac_f32_e32 v55, v56, v55
	v_div_scale_f32 v56, vcc, v71, v51, v71
	v_mul_f32_e32 v57, v56, v55
	v_fma_f32 v58, -v54, v57, v56
	v_fmac_f32_e32 v57, v58, v55
	v_fma_f32 v54, -v54, v57, v56
	v_div_fmas_f32 v54, v54, v55, v57
	v_div_fixup_f32 v51, v54, v51, v71
	v_div_scale_f32 v54, s[2:3], v50, v50, v70
	v_rcp_f32_e32 v55, v54
	s_nop 0
	v_fma_f32 v56, -v54, v55, 1.0
	v_fmac_f32_e32 v55, v56, v55
	v_div_scale_f32 v56, vcc, v70, v50, v70
	v_mul_f32_e32 v57, v56, v55
	v_fma_f32 v58, -v54, v57, v56
	v_fmac_f32_e32 v57, v58, v55
	v_fma_f32 v54, -v54, v57, v56
	v_div_fmas_f32 v54, v54, v55, v57
	v_div_fixup_f32 v50, v54, v50, v70
	v_pk_mul_f32 v[122:123], v[52:53], v[50:51]
	s_nop 0
	v_pk_fma_f32 v[48:49], v[122:123], v[122:123], v[48:49]
	v_mul_f32_e32 v50, v123, v123
	v_pk_add_f32 v[126:127], v[50:51], v[48:49] op_sel_hi:[0,1]
	s_waitcnt vmcnt(7)
	v_pk_fma_f32 v[32:33], v[32:33], v[124:125], v[186:187] op_sel_hi:[1,0,1]
	s_waitcnt vmcnt(6)
	v_mul_f32_e32 v103, 0xbfb8aa3b, v190
	v_fma_f32 v105, v190, s43, -v103
	v_rndne_f32_e32 v107, v103
	v_fmac_f32_e32 v105, 0xb2a5705f, v190
	v_sub_f32_e32 v103, v103, v107
	v_add_f32_e32 v103, v103, v105
	v_exp_f32_e32 v103, v103
	v_cvt_i32_f32_e32 v105, v107
	v_cmp_nlt_f32_e32 vcc, s34, v190
	v_ldexp_f32 v103, v103, v105
	s_nop 0
	v_cndmask_b32_e32 v103, 0, v103, vcc
	v_cmp_ngt_f32_e32 vcc, s35, v190
	s_nop 1
	v_cndmask_b32_e32 v128, v179, v103, vcc
	v_mul_f32_e32 v103, 0xbfb8aa3b, v191
	v_fma_f32 v105, v191, s43, -v103
	v_rndne_f32_e32 v107, v103
	v_fmac_f32_e32 v105, 0xb2a5705f, v191
	v_sub_f32_e32 v103, v103, v107
	v_add_f32_e32 v103, v103, v105
	v_exp_f32_e32 v103, v103
	v_cvt_i32_f32_e32 v105, v107
	v_cmp_nlt_f32_e32 vcc, s34, v191
	v_ldexp_f32 v103, v103, v105
	s_nop 0
	v_cndmask_b32_e32 v103, 0, v103, vcc
	v_cmp_ngt_f32_e32 vcc, s35, v191
	s_nop 1
	v_cndmask_b32_e32 v129, v179, v103, vcc
	v_pk_add_f32 v[68:69], v[128:129], 1.0 op_sel_hi:[1,0]
	s_nop 0
	v_div_scale_f32 v103, s[2:3], v69, v69, v191
	v_rcp_f32_e32 v105, v103
	s_nop 0
	v_fma_f32 v107, -v103, v105, 1.0
	v_fmac_f32_e32 v105, v107, v105
	v_div_scale_f32 v107, vcc, v191, v69, v191
	v_mul_f32_e32 v109, v107, v105
	v_fma_f32 v125, -v103, v109, v107
	v_fmac_f32_e32 v109, v125, v105
	v_fma_f32 v103, -v103, v109, v107
	v_div_fmas_f32 v103, v103, v105, v109
	v_div_fixup_f32 v65, v103, v69, v191
	v_div_scale_f32 v69, s[2:3], v68, v68, v190
	v_rcp_f32_e32 v103, v69
	v_pk_fma_f32 v[34:35], v[34:35], v[124:125], v[188:189] op_sel_hi:[1,0,1]
	s_waitcnt vmcnt(5)
	v_pk_fma_f32 v[36:37], v[36:37], v[124:125], v[194:195] op_sel_hi:[1,0,1]
	v_fma_f32 v105, -v69, v103, 1.0
	v_fmac_f32_e32 v103, v105, v103
	v_div_scale_f32 v105, vcc, v190, v68, v190
	v_mul_f32_e32 v107, v105, v103
	v_fma_f32 v109, -v69, v107, v105
	v_fmac_f32_e32 v107, v109, v103
	v_fma_f32 v69, -v69, v107, v105
	v_div_fmas_f32 v69, v69, v103, v107
	v_div_fixup_f32 v64, v69, v68, v190
	v_pk_mul_f32 v[64:65], v[32:33], v[64:65]
	v_cmp_nlt_f32_e32 vcc, s34, v192
	v_pk_fma_f32 v[32:33], v[64:65], v[64:65], v[126:127]
	v_mul_f32_e32 v68, v65, v65
	v_pk_add_f32 v[32:33], v[68:69], v[32:33] op_sel_hi:[0,1]
	v_mul_f32_e32 v68, 0xbfb8aa3b, v192
	v_fma_f32 v69, v192, s43, -v68
	v_rndne_f32_e32 v103, v68
	v_fmac_f32_e32 v69, 0xb2a5705f, v192
	v_sub_f32_e32 v68, v68, v103
	v_add_f32_e32 v68, v68, v69
	v_exp_f32_e32 v68, v68
	v_cvt_i32_f32_e32 v69, v103
	v_ldexp_f32 v68, v68, v69
	v_mul_f32_e32 v69, 0xbfb8aa3b, v193
	v_fma_f32 v103, v193, s43, -v69
	v_rndne_f32_e32 v105, v69
	v_fmac_f32_e32 v103, 0xb2a5705f, v193
	v_sub_f32_e32 v69, v69, v105
	v_add_f32_e32 v69, v69, v103
	v_exp_f32_e32 v69, v69
	v_cvt_i32_f32_e32 v103, v105
	v_cndmask_b32_e32 v68, 0, v68, vcc
	v_cmp_ngt_f32_e32 vcc, s35, v192
	v_ldexp_f32 v69, v69, v103
	s_nop 0
	v_cndmask_b32_e32 v68, v179, v68, vcc
	v_cmp_nlt_f32_e32 vcc, s34, v193
	s_nop 1
	v_cndmask_b32_e32 v69, 0, v69, vcc
	v_cmp_ngt_f32_e32 vcc, s35, v193
	s_nop 1
	v_cndmask_b32_e32 v69, v179, v69, vcc
	v_pk_add_f32 v[68:69], v[68:69], 1.0 op_sel_hi:[1,0]
	s_nop 0
	v_div_scale_f32 v70, s[2:3], v69, v69, v193
	v_rcp_f32_e32 v71, v70
	s_nop 0
	v_fma_f32 v103, -v70, v71, 1.0
	v_fmac_f32_e32 v71, v103, v71
	v_div_scale_f32 v103, vcc, v193, v69, v193
	v_mul_f32_e32 v105, v103, v71
	v_fma_f32 v107, -v70, v105, v103
	v_fmac_f32_e32 v105, v107, v71
	v_fma_f32 v70, -v70, v105, v103
	v_div_fmas_f32 v70, v70, v71, v105
	v_div_fixup_f32 v67, v70, v69, v193
	v_div_scale_f32 v69, s[2:3], v68, v68, v192
	v_rcp_f32_e32 v70, v69
	s_nop 0
	v_fma_f32 v71, -v69, v70, 1.0
	v_fmac_f32_e32 v70, v71, v70
	v_div_scale_f32 v71, vcc, v192, v68, v192
	v_mul_f32_e32 v103, v71, v70
	v_fma_f32 v105, -v69, v103, v71
	v_fmac_f32_e32 v103, v105, v70
	v_fma_f32 v69, -v69, v103, v71
	v_div_fmas_f32 v69, v69, v70, v103
	v_div_fixup_f32 v66, v69, v68, v192
	v_pk_mul_f32 v[66:67], v[34:35], v[66:67]
	s_waitcnt vmcnt(4)
	v_cmp_nlt_f32_e32 vcc, s34, v198
	v_pk_fma_f32 v[32:33], v[66:67], v[66:67], v[32:33]
	v_mul_f32_e32 v34, v67, v67
	v_pk_add_f32 v[32:33], v[34:35], v[32:33] op_sel_hi:[0,1]
	v_mul_f32_e32 v34, 0xbfb8aa3b, v198
	v_fma_f32 v35, v198, s43, -v34
	v_rndne_f32_e32 v68, v34
	v_fmac_f32_e32 v35, 0xb2a5705f, v198
	v_sub_f32_e32 v34, v34, v68
	v_add_f32_e32 v34, v34, v35
	v_exp_f32_e32 v34, v34
	v_cvt_i32_f32_e32 v35, v68
	v_ldexp_f32 v34, v34, v35
	v_mul_f32_e32 v35, 0xbfb8aa3b, v199
	v_fma_f32 v68, v199, s43, -v35
	v_rndne_f32_e32 v69, v35
	v_fmac_f32_e32 v68, 0xb2a5705f, v199
	v_sub_f32_e32 v35, v35, v69
	v_add_f32_e32 v35, v35, v68
	v_exp_f32_e32 v35, v35
	v_cvt_i32_f32_e32 v68, v69
	v_cndmask_b32_e32 v34, 0, v34, vcc
	v_cmp_ngt_f32_e32 vcc, s35, v198
	v_ldexp_f32 v35, v35, v68
	s_nop 0
	v_cndmask_b32_e32 v34, v179, v34, vcc
	v_cmp_nlt_f32_e32 vcc, s34, v199
	s_nop 1
	v_cndmask_b32_e32 v35, 0, v35, vcc
	v_cmp_ngt_f32_e32 vcc, s35, v199
	s_nop 1
	v_cndmask_b32_e32 v35, v179, v35, vcc
	v_pk_add_f32 v[34:35], v[34:35], 1.0 op_sel_hi:[1,0]
	s_nop 0
	v_div_scale_f32 v60, s[2:3], v35, v35, v199
	v_rcp_f32_e32 v61, v60
	s_nop 0
	v_fma_f32 v68, -v60, v61, 1.0
	v_fmac_f32_e32 v61, v68, v61
	v_div_scale_f32 v68, vcc, v199, v35, v199
	v_mul_f32_e32 v69, v68, v61
	v_fma_f32 v70, -v60, v69, v68
	v_fmac_f32_e32 v69, v70, v61
	v_fma_f32 v60, -v60, v69, v68
	v_div_fmas_f32 v60, v60, v61, v69
	v_div_fixup_f32 v35, v60, v35, v199
	v_div_scale_f32 v57, s[2:3], v34, v34, v198
	v_rcp_f32_e32 v60, v57
	s_nop 0
	v_fma_f32 v61, -v57, v60, 1.0
	v_fmac_f32_e32 v60, v61, v60
	v_div_scale_f32 v61, vcc, v198, v34, v198
	v_mul_f32_e32 v68, v61, v60
	v_fma_f32 v69, -v57, v68, v61
	v_fmac_f32_e32 v68, v69, v60
	v_fma_f32 v57, -v57, v68, v61
	v_div_fmas_f32 v57, v57, v60, v68
	v_div_fixup_f32 v34, v57, v34, v198
	v_pk_mul_f32 v[56:57], v[36:37], v[34:35]
	v_cmp_nlt_f32_e32 vcc, s34, v200
	v_pk_fma_f32 v[32:33], v[56:57], v[56:57], v[32:33]
	v_mul_f32_e32 v34, v57, v57
	v_pk_add_f32 v[32:33], v[34:35], v[32:33] op_sel_hi:[0,1]
	v_mul_f32_e32 v34, 0xbfb8aa3b, v200
	v_fma_f32 v35, v200, s43, -v34
	v_rndne_f32_e32 v36, v34
	v_fmac_f32_e32 v35, 0xb2a5705f, v200
	v_sub_f32_e32 v34, v34, v36
	v_add_f32_e32 v34, v34, v35
	v_exp_f32_e32 v34, v34
	v_cvt_i32_f32_e32 v35, v36
	v_ldexp_f32 v34, v34, v35
	v_mul_f32_e32 v35, 0xbfb8aa3b, v201
	v_fma_f32 v36, v201, s43, -v35
	v_rndne_f32_e32 v37, v35
	v_fmac_f32_e32 v36, 0xb2a5705f, v201
	v_sub_f32_e32 v35, v35, v37
	v_add_f32_e32 v35, v35, v36
	v_exp_f32_e32 v35, v35
	v_cvt_i32_f32_e32 v36, v37
	v_cndmask_b32_e32 v34, 0, v34, vcc
	v_cmp_ngt_f32_e32 vcc, s35, v200
	v_ldexp_f32 v35, v35, v36
	s_nop 0
	v_cndmask_b32_e32 v34, v179, v34, vcc
	v_cmp_nlt_f32_e32 vcc, s34, v201
	v_pk_fma_f32 v[36:37], v[38:39], v[124:125], v[196:197] op_sel_hi:[1,0,1]
	s_nop 0
	v_cndmask_b32_e32 v35, 0, v35, vcc
	v_cmp_ngt_f32_e32 vcc, s35, v201
	s_nop 1
	v_cndmask_b32_e32 v35, v179, v35, vcc
	v_pk_add_f32 v[34:35], v[34:35], 1.0 op_sel_hi:[1,0]
	s_nop 0
	v_div_scale_f32 v38, s[2:3], v35, v35, v201
	v_rcp_f32_e32 v39, v38
	s_nop 0
	v_fma_f32 v60, -v38, v39, 1.0
	v_fmac_f32_e32 v39, v60, v39
	v_div_scale_f32 v60, vcc, v201, v35, v201
	v_mul_f32_e32 v61, v60, v39
	v_fma_f32 v62, -v38, v61, v60
	v_fmac_f32_e32 v61, v62, v39
	v_fma_f32 v38, -v38, v61, v60
	v_div_fmas_f32 v38, v38, v39, v61
	v_div_fixup_f32 v35, v38, v35, v201
	v_div_scale_f32 v38, s[2:3], v34, v34, v200
	v_rcp_f32_e32 v39, v38
	s_nop 0
	v_fma_f32 v59, -v38, v39, 1.0
	v_fmac_f32_e32 v39, v59, v39
	v_div_scale_f32 v59, vcc, v200, v34, v200
	v_mul_f32_e32 v60, v59, v39
	v_fma_f32 v61, -v38, v60, v59
	v_fmac_f32_e32 v60, v61, v39
	v_fma_f32 v38, -v38, v60, v59
	v_div_fmas_f32 v38, v38, v39, v60
	v_div_fixup_f32 v34, v38, v34, v200
	v_pk_mul_f32 v[58:59], v[36:37], v[34:35]
	s_waitcnt vmcnt(2)
	v_cmp_nlt_f32_e32 vcc, s34, v206
	v_pk_fma_f32 v[32:33], v[58:59], v[58:59], v[32:33]
	v_mul_f32_e32 v34, v59, v59
	v_pk_add_f32 v[32:33], v[34:35], v[32:33] op_sel_hi:[0,1]
	v_mul_f32_e32 v34, 0xbfb8aa3b, v206
	v_fma_f32 v35, v206, s43, -v34
	v_rndne_f32_e32 v36, v34
	v_fmac_f32_e32 v35, 0xb2a5705f, v206
	v_sub_f32_e32 v34, v34, v36
	v_add_f32_e32 v34, v34, v35
	v_exp_f32_e32 v34, v34
	v_cvt_i32_f32_e32 v35, v36
	v_ldexp_f32 v34, v34, v35
	v_mul_f32_e32 v35, 0xbfb8aa3b, v207
	v_fma_f32 v36, v207, s43, -v35
	v_rndne_f32_e32 v37, v35
	v_fmac_f32_e32 v36, 0xb2a5705f, v207
	v_sub_f32_e32 v35, v35, v37
	v_add_f32_e32 v35, v35, v36
	v_exp_f32_e32 v35, v35
	v_cvt_i32_f32_e32 v36, v37
	v_cndmask_b32_e32 v34, 0, v34, vcc
	v_cmp_ngt_f32_e32 vcc, s35, v206
	v_ldexp_f32 v35, v35, v36
	s_nop 0
	v_cndmask_b32_e32 v34, v179, v34, vcc
	v_cmp_nlt_f32_e32 vcc, s34, v207
	v_pk_fma_f32 v[36:37], v[40:41], v[124:125], v[202:203] op_sel_hi:[1,0,1]
	s_nop 0
	v_cndmask_b32_e32 v35, 0, v35, vcc
	v_cmp_ngt_f32_e32 vcc, s35, v207
	s_nop 1
	v_cndmask_b32_e32 v35, v179, v35, vcc
	v_pk_add_f32 v[34:35], v[34:35], 1.0 op_sel_hi:[1,0]
	s_nop 0
	v_div_scale_f32 v38, s[2:3], v35, v35, v207
	v_rcp_f32_e32 v39, v38
	s_nop 0
	v_fma_f32 v40, -v38, v39, 1.0
	v_fmac_f32_e32 v39, v40, v39
	v_div_scale_f32 v40, vcc, v207, v35, v207
	v_mul_f32_e32 v41, v40, v39
	v_fma_f32 v52, -v38, v41, v40
	v_fmac_f32_e32 v41, v52, v39
	v_fma_f32 v38, -v38, v41, v40
	v_div_fmas_f32 v38, v38, v39, v41
	v_div_fixup_f32 v35, v38, v35, v207
	v_div_scale_f32 v38, s[2:3], v34, v34, v206
	v_rcp_f32_e32 v39, v38
	s_nop 0
	v_fma_f32 v40, -v38, v39, 1.0
	v_fmac_f32_e32 v39, v40, v39
	v_div_scale_f32 v40, vcc, v206, v34, v206
	v_mul_f32_e32 v41, v40, v39
	v_fma_f32 v49, -v38, v41, v40
	v_fmac_f32_e32 v41, v49, v39
	v_fma_f32 v38, -v38, v41, v40
	v_div_fmas_f32 v38, v38, v39, v41
	v_div_fixup_f32 v34, v38, v34, v206
	v_pk_mul_f32 v[48:49], v[36:37], v[34:35]
	v_cmp_nlt_f32_e32 vcc, s34, v208
	v_pk_fma_f32 v[32:33], v[48:49], v[48:49], v[32:33]
	v_mul_f32_e32 v34, v49, v49
	v_pk_add_f32 v[32:33], v[34:35], v[32:33] op_sel_hi:[0,1]
	v_mul_f32_e32 v34, 0xbfb8aa3b, v208
	v_fma_f32 v35, v208, s43, -v34
	v_rndne_f32_e32 v36, v34
	v_fmac_f32_e32 v35, 0xb2a5705f, v208
	v_sub_f32_e32 v34, v34, v36
	v_add_f32_e32 v34, v34, v35
	v_exp_f32_e32 v34, v34
	v_cvt_i32_f32_e32 v35, v36
	v_ldexp_f32 v34, v34, v35
	v_mul_f32_e32 v35, 0xbfb8aa3b, v209
	v_fma_f32 v36, v209, s43, -v35
	v_rndne_f32_e32 v37, v35
	v_fmac_f32_e32 v36, 0xb2a5705f, v209
	v_sub_f32_e32 v35, v35, v37
	v_add_f32_e32 v35, v35, v36
	v_exp_f32_e32 v35, v35
	v_cvt_i32_f32_e32 v36, v37
	v_cndmask_b32_e32 v34, 0, v34, vcc
	v_cmp_ngt_f32_e32 vcc, s35, v208
	v_ldexp_f32 v35, v35, v36
	s_nop 0
	v_cndmask_b32_e32 v34, v179, v34, vcc
	v_cmp_nlt_f32_e32 vcc, s34, v209
	v_pk_fma_f32 v[36:37], v[42:43], v[124:125], v[204:205] op_sel_hi:[1,0,1]
	s_nop 0
	v_cndmask_b32_e32 v35, 0, v35, vcc
	v_cmp_ngt_f32_e32 vcc, s35, v209
	s_nop 1
	v_cndmask_b32_e32 v35, v179, v35, vcc
	v_pk_add_f32 v[34:35], v[34:35], 1.0 op_sel_hi:[1,0]
	s_nop 0
	v_div_scale_f32 v38, s[2:3], v35, v35, v209
	v_rcp_f32_e32 v39, v38
	s_nop 0
	v_fma_f32 v40, -v38, v39, 1.0
	v_fmac_f32_e32 v39, v40, v39
	v_div_scale_f32 v40, vcc, v209, v35, v209
	v_mul_f32_e32 v41, v40, v39
	v_fma_f32 v42, -v38, v41, v40
	v_fmac_f32_e32 v41, v42, v39
	v_fma_f32 v38, -v38, v41, v40
	v_div_fmas_f32 v38, v38, v39, v41
	v_div_fixup_f32 v35, v38, v35, v209
	v_div_scale_f32 v38, s[2:3], v34, v34, v208
	v_rcp_f32_e32 v39, v38
	s_nop 0
	v_fma_f32 v40, -v38, v39, 1.0
	v_fmac_f32_e32 v39, v40, v39
	v_div_scale_f32 v40, vcc, v208, v34, v208
	v_mul_f32_e32 v41, v40, v39
	v_fma_f32 v42, -v38, v41, v40
	v_fmac_f32_e32 v41, v42, v39
	v_fma_f32 v38, -v38, v41, v40
	v_div_fmas_f32 v38, v38, v39, v41
	v_div_fixup_f32 v34, v38, v34, v208
	v_pk_mul_f32 v[52:53], v[36:37], v[34:35]
	s_waitcnt vmcnt(0)
	v_cmp_nlt_f32_e32 vcc, s34, v214
	v_pk_fma_f32 v[32:33], v[52:53], v[52:53], v[32:33]
	v_mul_f32_e32 v34, v53, v53
	v_pk_add_f32 v[32:33], v[34:35], v[32:33] op_sel_hi:[0,1]
	v_mul_f32_e32 v34, 0xbfb8aa3b, v214
	v_fma_f32 v35, v214, s43, -v34
	v_rndne_f32_e32 v36, v34
	v_fmac_f32_e32 v35, 0xb2a5705f, v214
	v_sub_f32_e32 v34, v34, v36
	v_add_f32_e32 v34, v34, v35
	v_exp_f32_e32 v34, v34
	v_cvt_i32_f32_e32 v35, v36
	v_ldexp_f32 v34, v34, v35
	v_mul_f32_e32 v35, 0xbfb8aa3b, v215
	v_fma_f32 v36, v215, s43, -v35
	v_rndne_f32_e32 v37, v35
	v_fmac_f32_e32 v36, 0xb2a5705f, v215
	v_sub_f32_e32 v35, v35, v37
	v_add_f32_e32 v35, v35, v36
	v_exp_f32_e32 v35, v35
	v_cvt_i32_f32_e32 v36, v37
	v_cndmask_b32_e32 v34, 0, v34, vcc
	v_cmp_ngt_f32_e32 vcc, s35, v214
	v_ldexp_f32 v35, v35, v36
	s_nop 0
	v_cndmask_b32_e32 v34, v179, v34, vcc
	v_cmp_nlt_f32_e32 vcc, s34, v215
	v_pk_fma_f32 v[36:37], v[44:45], v[124:125], v[210:211] op_sel_hi:[1,0,1]
	s_nop 0
	v_cndmask_b32_e32 v35, 0, v35, vcc
	v_cmp_ngt_f32_e32 vcc, s35, v215
	s_nop 1
	v_cndmask_b32_e32 v35, v179, v35, vcc
	v_pk_add_f32 v[34:35], v[34:35], 1.0 op_sel_hi:[1,0]
	s_nop 0
	v_div_scale_f32 v38, s[2:3], v35, v35, v215
	v_rcp_f32_e32 v39, v38
	s_nop 0
	v_fma_f32 v40, -v38, v39, 1.0
	v_fmac_f32_e32 v39, v40, v39
	v_div_scale_f32 v40, vcc, v215, v35, v215
	v_mul_f32_e32 v41, v40, v39
	v_fma_f32 v42, -v38, v41, v40
	v_fmac_f32_e32 v41, v42, v39
	v_fma_f32 v38, -v38, v41, v40
	v_div_fmas_f32 v38, v38, v39, v41
	v_div_fixup_f32 v35, v38, v35, v215
	v_div_scale_f32 v38, s[2:3], v34, v34, v214
	v_rcp_f32_e32 v39, v38
	s_nop 0
	v_fma_f32 v40, -v38, v39, 1.0
	v_fmac_f32_e32 v39, v40, v39
	v_div_scale_f32 v40, vcc, v214, v34, v214
	v_mul_f32_e32 v41, v40, v39
	v_fma_f32 v42, -v38, v41, v40
	v_fmac_f32_e32 v41, v42, v39
	v_fma_f32 v38, -v38, v41, v40
	v_div_fmas_f32 v38, v38, v39, v41
	v_div_fixup_f32 v34, v38, v34, v214
	v_pk_mul_f32 v[60:61], v[36:37], v[34:35]
	v_cmp_nlt_f32_e32 vcc, s34, v216
	v_pk_fma_f32 v[32:33], v[60:61], v[60:61], v[32:33]
	v_mul_f32_e32 v34, v61, v61
	v_pk_add_f32 v[32:33], v[34:35], v[32:33] op_sel_hi:[0,1]
	v_mul_f32_e32 v34, 0xbfb8aa3b, v216
	v_fma_f32 v35, v216, s43, -v34
	v_rndne_f32_e32 v36, v34
	v_fmac_f32_e32 v35, 0xb2a5705f, v216
	v_sub_f32_e32 v34, v34, v36
	v_add_f32_e32 v34, v34, v35
	v_exp_f32_e32 v34, v34
	v_cvt_i32_f32_e32 v35, v36
	v_ldexp_f32 v34, v34, v35
	v_mul_f32_e32 v35, 0xbfb8aa3b, v217
	v_fma_f32 v36, v217, s43, -v35
	v_rndne_f32_e32 v37, v35
	v_fmac_f32_e32 v36, 0xb2a5705f, v217
	v_sub_f32_e32 v35, v35, v37
	v_add_f32_e32 v35, v35, v36
	v_exp_f32_e32 v35, v35
	v_cvt_i32_f32_e32 v36, v37
	v_cndmask_b32_e32 v34, 0, v34, vcc
	v_cmp_ngt_f32_e32 vcc, s35, v216
	v_ldexp_f32 v35, v35, v36
	s_nop 0
	v_cndmask_b32_e32 v34, v179, v34, vcc
	v_cmp_nlt_f32_e32 vcc, s34, v217
	v_pk_fma_f32 v[36:37], v[46:47], v[124:125], v[212:213] op_sel_hi:[1,0,1]
	s_nop 0
	v_cndmask_b32_e32 v35, 0, v35, vcc
	v_cmp_ngt_f32_e32 vcc, s35, v217
	s_nop 1
	v_cndmask_b32_e32 v35, v179, v35, vcc
	v_pk_add_f32 v[34:35], v[34:35], 1.0 op_sel_hi:[1,0]
	s_nop 0
	v_div_scale_f32 v38, s[2:3], v35, v35, v217
	v_rcp_f32_e32 v39, v38
	s_nop 0
	v_fma_f32 v40, -v38, v39, 1.0
	v_fmac_f32_e32 v39, v40, v39
	v_div_scale_f32 v40, vcc, v217, v35, v217
	v_mul_f32_e32 v41, v40, v39
	v_fma_f32 v42, -v38, v41, v40
	v_fmac_f32_e32 v41, v42, v39
	v_fma_f32 v38, -v38, v41, v40
	v_div_fmas_f32 v38, v38, v39, v41
	v_div_fixup_f32 v35, v38, v35, v217
	v_div_scale_f32 v38, s[2:3], v34, v34, v216
	v_rcp_f32_e32 v39, v38
	s_nop 0
	v_fma_f32 v40, -v38, v39, 1.0
	v_fmac_f32_e32 v39, v40, v39
	v_div_scale_f32 v40, vcc, v216, v34, v216
	v_mul_f32_e32 v41, v40, v39
	v_fma_f32 v42, -v38, v41, v40
	v_fmac_f32_e32 v41, v42, v39
	v_fma_f32 v38, -v38, v41, v40
	v_div_fmas_f32 v38, v38, v39, v41
	v_div_fixup_f32 v34, v38, v34, v216
	v_pk_mul_f32 v[78:79], v[36:37], v[34:35]
	s_nop 0
	v_pk_fma_f32 v[32:33], v[78:79], v[78:79], v[32:33]
	v_mul_f32_e32 v34, v79, v79
	v_pk_add_f32 v[32:33], v[34:35], v[32:33] op_sel_hi:[0,1]
	v_mov_b32_e32 v33, v32
	s_nop 1
	v_permlane32_swap_b32_e32 v32, v33
	s_and_saveexec_b64 s[14:15], s[48:49]
	v_add_f32_e32 v32, v32, v33
	ds_write_b32 v97, v32
	s_or_b64 exec, exec, s[14:15]
	v_mov_b32_e32 v33, s5
	v_or_b32_e32 v32, s4, v92
	v_lshlrev_b64 v[34:35], 5, v[32:33]
	v_lshl_add_u64 v[34:35], s[8:9], 0, v[34:35]
	global_load_dword v143, v[34:35], off
	v_mad_u64_u32 v[132:133], s[2:3], v32, s42, v[98:99]
	v_lshlrev_b64 v[50:51], 11, v[32:33]
	s_mul_i32 s2, s5, 0x2800
	v_lshl_add_u64 v[130:131], v[94:95], 0, v[50:51]
	v_add_u32_e32 v133, s2, v133
	global_load_dwordx4 v[70:73], v[130:131], off
	global_load_dwordx4 v[74:77], v[132:133], off
	global_load_dwordx4 v[134:137], v[130:131], off offset:32
	global_load_dwordx4 v[138:141], v[132:133], off offset:32
	global_load_dwordx4 v[44:47], v[130:131], off offset:64
	global_load_dwordx4 v[40:43], v[132:133], off offset:64
	global_load_dwordx4 v[36:39], v[130:131], off offset:96
	global_load_dwordx4 v[32:35], v[132:133], off offset:96
	s_waitcnt vmcnt(8)
	v_exp_f32_e32 v126, v143
	s_waitcnt vmcnt(7)
	v_pk_fma_f32 v[16:17], v[16:17], v[126:127], v[70:71] op_sel_hi:[1,0,1]
	v_pk_fma_f32 v[18:19], v[18:19], v[126:127], v[72:73] op_sel_hi:[1,0,1]
	s_waitcnt vmcnt(6)
	v_mul_f32_e32 v54, 0xbfb8aa3b, v74
	v_fma_f32 v55, v74, s43, -v54
	v_rndne_f32_e32 v62, v54
	v_fmac_f32_e32 v55, 0xb2a5705f, v74
	v_sub_f32_e32 v54, v54, v62
	v_add_f32_e32 v54, v54, v55
	v_exp_f32_e32 v54, v54
	v_cvt_i32_f32_e32 v55, v62
	v_cmp_nlt_f32_e32 vcc, s34, v74
	s_waitcnt vmcnt(5)
	v_pk_fma_f32 v[20:21], v[20:21], v[126:127], v[134:135] op_sel_hi:[1,0,1]
	v_ldexp_f32 v54, v54, v55
	v_mul_f32_e32 v55, 0xbfb8aa3b, v75
	v_fma_f32 v62, v75, s43, -v55
	v_rndne_f32_e32 v63, v55
	v_fmac_f32_e32 v62, 0xb2a5705f, v75
	v_sub_f32_e32 v55, v55, v63
	v_add_f32_e32 v55, v55, v62
	v_exp_f32_e32 v55, v55
	v_cvt_i32_f32_e32 v62, v63
	v_cndmask_b32_e32 v54, 0, v54, vcc
	v_cmp_ngt_f32_e32 vcc, s35, v74
	v_ldexp_f32 v55, v55, v62
	s_nop 0
	v_cndmask_b32_e32 v54, v179, v54, vcc
	v_cmp_nlt_f32_e32 vcc, s34, v75
	s_nop 1
	v_cndmask_b32_e32 v55, 0, v55, vcc
	v_cmp_ngt_f32_e32 vcc, s35, v75
	s_nop 1
	v_cndmask_b32_e32 v55, v179, v55, vcc
	v_pk_add_f32 v[54:55], v[54:55], 1.0 op_sel_hi:[1,0]
	s_nop 0
	v_div_scale_f32 v62, s[2:3], v55, v55, v75
	v_rcp_f32_e32 v63, v62
	s_nop 0
	v_fma_f32 v68, -v62, v63, 1.0
	v_fmac_f32_e32 v63, v68, v63
	v_div_scale_f32 v68, vcc, v75, v55, v75
	v_mul_f32_e32 v69, v68, v63
	v_fma_f32 v70, -v62, v69, v68
	v_fmac_f32_e32 v69, v70, v63
	v_fma_f32 v62, -v62, v69, v68
	v_div_fmas_f32 v62, v62, v63, v69
	v_div_fixup_f32 v55, v62, v55, v75
	v_div_scale_f32 v62, s[2:3], v54, v54, v74
	v_rcp_f32_e32 v63, v62
	s_nop 0
	v_fma_f32 v68, -v62, v63, 1.0
	v_fmac_f32_e32 v63, v68, v63
	v_div_scale_f32 v68, vcc, v74, v54, v74
	v_mul_f32_e32 v69, v68, v63
	v_fma_f32 v70, -v62, v69, v68
	v_fmac_f32_e32 v69, v70, v63
	v_fma_f32 v62, -v62, v69, v68
	v_div_fmas_f32 v62, v62, v63, v69
	v_div_fixup_f32 v54, v62, v54, v74
	v_pk_mul_f32 v[70:71], v[16:17], v[54:55]
	v_mul_f32_e32 v54, 0xbfb8aa3b, v76
	v_fma_f32 v55, v76, s43, -v54
	v_rndne_f32_e32 v62, v54
	v_fmac_f32_e32 v55, 0xb2a5705f, v76
	v_sub_f32_e32 v54, v54, v62
	v_add_f32_e32 v54, v54, v55
	v_exp_f32_e32 v54, v54
	v_cvt_i32_f32_e32 v55, v62
	v_cmp_nlt_f32_e32 vcc, s34, v76
	v_mul_f32_e32 v16, v71, v71
	v_pk_fma_f32 v[16:17], v[70:71], v[70:71], v[16:17] op_sel_hi:[1,1,0]
	v_ldexp_f32 v54, v54, v55
	v_mul_f32_e32 v55, 0xbfb8aa3b, v77
	v_fma_f32 v62, v77, s43, -v55
	v_rndne_f32_e32 v63, v55
	v_fmac_f32_e32 v62, 0xb2a5705f, v77
	v_sub_f32_e32 v55, v55, v63
	v_add_f32_e32 v55, v55, v62
	v_exp_f32_e32 v55, v55
	v_cvt_i32_f32_e32 v62, v63
	v_cndmask_b32_e32 v54, 0, v54, vcc
	v_cmp_ngt_f32_e32 vcc, s35, v76
	v_ldexp_f32 v55, v55, v62
	s_nop 0
	v_cndmask_b32_e32 v54, v179, v54, vcc
	v_cmp_nlt_f32_e32 vcc, s34, v77
	s_nop 1
	v_cndmask_b32_e32 v55, 0, v55, vcc
	v_cmp_ngt_f32_e32 vcc, s35, v77
	s_nop 1
	v_cndmask_b32_e32 v55, v179, v55, vcc
	v_pk_add_f32 v[54:55], v[54:55], 1.0 op_sel_hi:[1,0]
	s_nop 0
	v_div_scale_f32 v62, s[2:3], v55, v55, v77
	v_rcp_f32_e32 v63, v62
	s_nop 0
	v_fma_f32 v68, -v62, v63, 1.0
	v_fmac_f32_e32 v63, v68, v63
	v_div_scale_f32 v68, vcc, v77, v55, v77
	v_mul_f32_e32 v69, v68, v63
	v_fma_f32 v72, -v62, v69, v68
	v_fmac_f32_e32 v69, v72, v63
	v_fma_f32 v62, -v62, v69, v68
	v_div_fmas_f32 v62, v62, v63, v69
	v_div_fixup_f32 v55, v62, v55, v77
	v_div_scale_f32 v62, s[2:3], v54, v54, v76
	v_rcp_f32_e32 v63, v62
	s_nop 0
	v_fma_f32 v68, -v62, v63, 1.0
	v_fmac_f32_e32 v63, v68, v63
	v_div_scale_f32 v68, vcc, v76, v54, v76
	v_mul_f32_e32 v69, v68, v63
	v_fma_f32 v72, -v62, v69, v68
	v_fmac_f32_e32 v69, v72, v63
	v_fma_f32 v62, -v62, v69, v68
	v_div_fmas_f32 v62, v62, v63, v69
	v_div_fixup_f32 v54, v62, v54, v76
	v_pk_mul_f32 v[74:75], v[18:19], v[54:55]
	s_waitcnt vmcnt(4)
	v_cmp_nlt_f32_e32 vcc, s34, v138
	v_pk_fma_f32 v[16:17], v[74:75], v[74:75], v[16:17]
	v_mul_f32_e32 v18, v75, v75
	v_pk_add_f32 v[16:17], v[18:19], v[16:17] op_sel_hi:[0,1]
	v_mul_f32_e32 v18, 0xbfb8aa3b, v138
	v_fma_f32 v19, v138, s43, -v18
	v_rndne_f32_e32 v54, v18
	v_fmac_f32_e32 v19, 0xb2a5705f, v138
	v_sub_f32_e32 v18, v18, v54
	v_add_f32_e32 v18, v18, v19
	v_exp_f32_e32 v18, v18
	v_cvt_i32_f32_e32 v19, v54
	v_ldexp_f32 v18, v18, v19
	v_mul_f32_e32 v19, 0xbfb8aa3b, v139
	v_fma_f32 v54, v139, s43, -v19
	v_rndne_f32_e32 v55, v19
	v_fmac_f32_e32 v54, 0xb2a5705f, v139
	v_sub_f32_e32 v19, v19, v55
	v_add_f32_e32 v19, v19, v54
	v_exp_f32_e32 v19, v19
	v_cvt_i32_f32_e32 v54, v55
	v_cndmask_b32_e32 v18, 0, v18, vcc
	v_cmp_ngt_f32_e32 vcc, s35, v138
	v_ldexp_f32 v19, v19, v54
	s_nop 0
	v_cndmask_b32_e32 v18, v179, v18, vcc
	v_cmp_nlt_f32_e32 vcc, s34, v139
	s_nop 1
	v_cndmask_b32_e32 v19, 0, v19, vcc
	v_cmp_ngt_f32_e32 vcc, s35, v139
	s_nop 1
	v_cndmask_b32_e32 v19, v179, v19, vcc
	v_pk_add_f32 v[18:19], v[18:19], 1.0 op_sel_hi:[1,0]
	s_nop 0
	v_div_scale_f32 v54, s[2:3], v19, v19, v139
	v_rcp_f32_e32 v55, v54
	s_nop 0
	v_fma_f32 v62, -v54, v55, 1.0
	v_fmac_f32_e32 v55, v62, v55
	v_div_scale_f32 v62, vcc, v139, v19, v139
	v_mul_f32_e32 v63, v62, v55
	v_fma_f32 v68, -v54, v63, v62
	v_fmac_f32_e32 v63, v68, v55
	v_fma_f32 v54, -v54, v63, v62
	v_div_fmas_f32 v54, v54, v55, v63
	v_div_fixup_f32 v19, v54, v19, v139
	v_div_scale_f32 v54, s[2:3], v18, v18, v138
	v_rcp_f32_e32 v55, v54
	s_nop 0
	v_fma_f32 v62, -v54, v55, 1.0
	v_fmac_f32_e32 v55, v62, v55
	v_div_scale_f32 v62, vcc, v138, v18, v138
	v_mul_f32_e32 v63, v62, v55
	v_fma_f32 v68, -v54, v63, v62
	v_fmac_f32_e32 v63, v68, v55
	v_fma_f32 v54, -v54, v63, v62
	v_div_fmas_f32 v54, v54, v55, v63
	v_div_fixup_f32 v18, v54, v18, v138
	v_pk_mul_f32 v[54:55], v[20:21], v[18:19]
	v_cmp_nlt_f32_e32 vcc, s34, v140
	v_pk_fma_f32 v[16:17], v[54:55], v[54:55], v[16:17]
	v_mul_f32_e32 v18, v55, v55
	v_pk_add_f32 v[16:17], v[18:19], v[16:17] op_sel_hi:[0,1]
	v_mul_f32_e32 v18, 0xbfb8aa3b, v140
	v_fma_f32 v19, v140, s43, -v18
	v_rndne_f32_e32 v20, v18
	v_fmac_f32_e32 v19, 0xb2a5705f, v140
	v_sub_f32_e32 v18, v18, v20
	v_add_f32_e32 v18, v18, v19
	v_exp_f32_e32 v18, v18
	v_cvt_i32_f32_e32 v19, v20
	v_ldexp_f32 v18, v18, v19
	v_mul_f32_e32 v19, 0xbfb8aa3b, v141
	v_fma_f32 v20, v141, s43, -v19
	v_rndne_f32_e32 v21, v19
	v_fmac_f32_e32 v20, 0xb2a5705f, v141
	v_sub_f32_e32 v19, v19, v21
	v_add_f32_e32 v19, v19, v20
	v_exp_f32_e32 v19, v19
	v_cvt_i32_f32_e32 v20, v21
	v_cndmask_b32_e32 v18, 0, v18, vcc
	v_cmp_ngt_f32_e32 vcc, s35, v140
	v_ldexp_f32 v19, v19, v20
	s_nop 0
	v_cndmask_b32_e32 v18, v179, v18, vcc
	v_cmp_nlt_f32_e32 vcc, s34, v141
	v_pk_fma_f32 v[20:21], v[22:23], v[126:127], v[136:137] op_sel_hi:[1,0,1]
	s_nop 0
	v_cndmask_b32_e32 v19, 0, v19, vcc
	v_cmp_ngt_f32_e32 vcc, s35, v141
	s_nop 1
	v_cndmask_b32_e32 v19, v179, v19, vcc
	v_pk_add_f32 v[18:19], v[18:19], 1.0 op_sel_hi:[1,0]
	s_nop 0
	v_div_scale_f32 v22, s[2:3], v19, v19, v141
	v_rcp_f32_e32 v23, v22
	s_nop 0
	v_fma_f32 v62, -v22, v23, 1.0
	v_fmac_f32_e32 v23, v62, v23
	v_div_scale_f32 v62, vcc, v141, v19, v141
	v_mul_f32_e32 v63, v62, v23
	v_fma_f32 v68, -v22, v63, v62
	v_fmac_f32_e32 v63, v68, v23
	v_fma_f32 v22, -v22, v63, v62
	v_div_fmas_f32 v22, v22, v23, v63
	v_div_fixup_f32 v19, v22, v19, v141
	v_div_scale_f32 v22, s[2:3], v18, v18, v140
	v_rcp_f32_e32 v23, v22
	s_nop 0
	v_fma_f32 v62, -v22, v23, 1.0
	v_fmac_f32_e32 v23, v62, v23
	v_div_scale_f32 v62, vcc, v140, v18, v140
	v_mul_f32_e32 v63, v62, v23
	v_fma_f32 v68, -v22, v63, v62
	v_fmac_f32_e32 v63, v68, v23
	v_fma_f32 v22, -v22, v63, v62
	v_div_fmas_f32 v22, v22, v23, v63
	v_div_fixup_f32 v18, v22, v18, v140
	v_pk_mul_f32 v[62:63], v[20:21], v[18:19]
	s_waitcnt vmcnt(2)
	v_cmp_nlt_f32_e32 vcc, s34, v40
	v_pk_fma_f32 v[16:17], v[62:63], v[62:63], v[16:17]
	v_mul_f32_e32 v18, v63, v63
	v_pk_add_f32 v[16:17], v[18:19], v[16:17] op_sel_hi:[0,1]
	v_mul_f32_e32 v18, 0xbfb8aa3b, v40
	v_fma_f32 v19, v40, s43, -v18
	v_rndne_f32_e32 v20, v18
	v_fmac_f32_e32 v19, 0xb2a5705f, v40
	v_sub_f32_e32 v18, v18, v20
	v_add_f32_e32 v18, v18, v19
	v_exp_f32_e32 v18, v18
	v_cvt_i32_f32_e32 v19, v20
	v_ldexp_f32 v18, v18, v19
	v_mul_f32_e32 v19, 0xbfb8aa3b, v41
	v_fma_f32 v20, v41, s43, -v19
	v_rndne_f32_e32 v21, v19
	v_fmac_f32_e32 v20, 0xb2a5705f, v41
	v_sub_f32_e32 v19, v19, v21
	v_add_f32_e32 v19, v19, v20
	v_exp_f32_e32 v19, v19
	v_cvt_i32_f32_e32 v20, v21
	v_cndmask_b32_e32 v18, 0, v18, vcc
	v_cmp_ngt_f32_e32 vcc, s35, v40
	v_ldexp_f32 v19, v19, v20
	s_nop 0
	v_cndmask_b32_e32 v18, v179, v18, vcc
	v_cmp_nlt_f32_e32 vcc, s34, v41
	v_pk_fma_f32 v[20:21], v[24:25], v[126:127], v[44:45] op_sel_hi:[1,0,1]
	s_nop 0
	v_cndmask_b32_e32 v19, 0, v19, vcc
	v_cmp_ngt_f32_e32 vcc, s35, v41
	s_nop 1
	v_cndmask_b32_e32 v19, v179, v19, vcc
	v_pk_add_f32 v[18:19], v[18:19], 1.0 op_sel_hi:[1,0]
	s_nop 0
	v_div_scale_f32 v22, s[2:3], v19, v19, v41
	v_rcp_f32_e32 v23, v22
	s_nop 0
	v_fma_f32 v24, -v22, v23, 1.0
	v_fmac_f32_e32 v23, v24, v23
	v_div_scale_f32 v24, vcc, v41, v19, v41
	v_mul_f32_e32 v25, v24, v23
	v_fma_f32 v44, -v22, v25, v24
	v_fmac_f32_e32 v25, v44, v23
	v_fma_f32 v22, -v22, v25, v24
	v_div_fmas_f32 v22, v22, v23, v25
	v_div_fixup_f32 v19, v22, v19, v41
	v_div_scale_f32 v22, s[2:3], v18, v18, v40
	v_rcp_f32_e32 v23, v22
	s_nop 0
	v_fma_f32 v24, -v22, v23, 1.0
	v_fmac_f32_e32 v23, v24, v23
	v_div_scale_f32 v24, vcc, v40, v18, v40
	v_mul_f32_e32 v25, v24, v23
	v_fma_f32 v41, -v22, v25, v24
	v_fmac_f32_e32 v25, v41, v23
	v_fma_f32 v22, -v22, v25, v24
	v_div_fmas_f32 v22, v22, v23, v25
	v_div_fixup_f32 v18, v22, v18, v40
	v_pk_mul_f32 v[68:69], v[20:21], v[18:19]
	v_cmp_nlt_f32_e32 vcc, s34, v42
	v_pk_fma_f32 v[16:17], v[68:69], v[68:69], v[16:17]
	v_mul_f32_e32 v18, v69, v69
	v_pk_add_f32 v[16:17], v[18:19], v[16:17] op_sel_hi:[0,1]
	v_mul_f32_e32 v18, 0xbfb8aa3b, v42
	v_fma_f32 v19, v42, s43, -v18
	v_rndne_f32_e32 v20, v18
	v_fmac_f32_e32 v19, 0xb2a5705f, v42
	v_sub_f32_e32 v18, v18, v20
	v_add_f32_e32 v18, v18, v19
	v_exp_f32_e32 v18, v18
	v_cvt_i32_f32_e32 v19, v20
	v_ldexp_f32 v18, v18, v19
	v_mul_f32_e32 v19, 0xbfb8aa3b, v43
	v_fma_f32 v20, v43, s43, -v19
	v_rndne_f32_e32 v21, v19
	v_fmac_f32_e32 v20, 0xb2a5705f, v43
	v_sub_f32_e32 v19, v19, v21
	v_add_f32_e32 v19, v19, v20
	v_exp_f32_e32 v19, v19
	v_cvt_i32_f32_e32 v20, v21
	v_cndmask_b32_e32 v18, 0, v18, vcc
	v_cmp_ngt_f32_e32 vcc, s35, v42
	v_ldexp_f32 v19, v19, v20
	s_nop 0
	v_cndmask_b32_e32 v18, v179, v18, vcc
	v_cmp_nlt_f32_e32 vcc, s34, v43
	v_pk_fma_f32 v[20:21], v[26:27], v[126:127], v[46:47] op_sel_hi:[1,0,1]
	s_nop 0
	v_cndmask_b32_e32 v19, 0, v19, vcc
	v_cmp_ngt_f32_e32 vcc, s35, v43
	s_nop 1
	v_cndmask_b32_e32 v19, v179, v19, vcc
	v_pk_add_f32 v[18:19], v[18:19], 1.0 op_sel_hi:[1,0]
	s_nop 0
	v_div_scale_f32 v22, s[2:3], v19, v19, v43
	v_rcp_f32_e32 v23, v22
	s_nop 0
	v_fma_f32 v24, -v22, v23, 1.0
	v_fmac_f32_e32 v23, v24, v23
	v_div_scale_f32 v24, vcc, v43, v19, v43
	v_mul_f32_e32 v25, v24, v23
	v_fma_f32 v26, -v22, v25, v24
	v_fmac_f32_e32 v25, v26, v23
	v_fma_f32 v22, -v22, v25, v24
	v_div_fmas_f32 v22, v22, v23, v25
	v_div_fixup_f32 v19, v22, v19, v43
	v_div_scale_f32 v22, s[2:3], v18, v18, v42
	v_rcp_f32_e32 v23, v22
	s_nop 0
	v_fma_f32 v24, -v22, v23, 1.0
	v_fmac_f32_e32 v23, v24, v23
	v_div_scale_f32 v24, vcc, v42, v18, v42
	v_mul_f32_e32 v25, v24, v23
	v_fma_f32 v26, -v22, v25, v24
	v_fmac_f32_e32 v25, v26, v23
	v_fma_f32 v22, -v22, v25, v24
	v_div_fmas_f32 v22, v22, v23, v25
	v_div_fixup_f32 v18, v22, v18, v42
	v_pk_mul_f32 v[72:73], v[20:21], v[18:19]
	s_waitcnt vmcnt(0)
	v_cmp_nlt_f32_e32 vcc, s34, v32
	v_pk_fma_f32 v[16:17], v[72:73], v[72:73], v[16:17]
	v_mul_f32_e32 v18, v73, v73
	v_pk_add_f32 v[16:17], v[18:19], v[16:17] op_sel_hi:[0,1]
	v_mul_f32_e32 v18, 0xbfb8aa3b, v32
	v_fma_f32 v19, v32, s43, -v18
	v_rndne_f32_e32 v20, v18
	v_fmac_f32_e32 v19, 0xb2a5705f, v32
	v_sub_f32_e32 v18, v18, v20
	v_add_f32_e32 v18, v18, v19
	v_exp_f32_e32 v18, v18
	v_cvt_i32_f32_e32 v19, v20
	v_ldexp_f32 v18, v18, v19
	v_mul_f32_e32 v19, 0xbfb8aa3b, v33
	v_fma_f32 v20, v33, s43, -v19
	v_rndne_f32_e32 v21, v19
	v_fmac_f32_e32 v20, 0xb2a5705f, v33
	v_sub_f32_e32 v19, v19, v21
	v_add_f32_e32 v19, v19, v20
	v_exp_f32_e32 v19, v19
	v_cvt_i32_f32_e32 v20, v21
	v_cndmask_b32_e32 v18, 0, v18, vcc
	v_cmp_ngt_f32_e32 vcc, s35, v32
	v_ldexp_f32 v19, v19, v20
	s_nop 0
	v_cndmask_b32_e32 v18, v179, v18, vcc
	v_cmp_nlt_f32_e32 vcc, s34, v33
	v_pk_fma_f32 v[20:21], v[28:29], v[126:127], v[36:37] op_sel_hi:[1,0,1]
	s_nop 0
	v_cndmask_b32_e32 v19, 0, v19, vcc
	v_cmp_ngt_f32_e32 vcc, s35, v33
	s_nop 1
	v_cndmask_b32_e32 v19, v179, v19, vcc
	v_pk_add_f32 v[18:19], v[18:19], 1.0 op_sel_hi:[1,0]
	s_nop 0
	v_div_scale_f32 v22, s[2:3], v19, v19, v33
	v_rcp_f32_e32 v23, v22
	s_nop 0
	v_fma_f32 v24, -v22, v23, 1.0
	v_fmac_f32_e32 v23, v24, v23
	v_div_scale_f32 v24, vcc, v33, v19, v33
	v_mul_f32_e32 v25, v24, v23
	v_fma_f32 v26, -v22, v25, v24
	v_fmac_f32_e32 v25, v26, v23
	v_fma_f32 v22, -v22, v25, v24
	v_div_fmas_f32 v22, v22, v23, v25
	v_div_fixup_f32 v19, v22, v19, v33
	v_div_scale_f32 v22, s[2:3], v18, v18, v32
	v_rcp_f32_e32 v23, v22
	s_nop 0
	v_fma_f32 v24, -v22, v23, 1.0
	v_fmac_f32_e32 v23, v24, v23
	v_div_scale_f32 v24, vcc, v32, v18, v32
	v_mul_f32_e32 v25, v24, v23
	v_fma_f32 v26, -v22, v25, v24
	v_fmac_f32_e32 v25, v26, v23
	v_fma_f32 v22, -v22, v25, v24
	v_div_fmas_f32 v22, v22, v23, v25
	v_div_fixup_f32 v18, v22, v18, v32
	v_pk_mul_f32 v[76:77], v[20:21], v[18:19]
	v_cmp_nlt_f32_e32 vcc, s34, v34
	v_pk_fma_f32 v[16:17], v[76:77], v[76:77], v[16:17]
	v_mul_f32_e32 v18, v77, v77
	v_pk_add_f32 v[16:17], v[18:19], v[16:17] op_sel_hi:[0,1]
	v_mul_f32_e32 v18, 0xbfb8aa3b, v34
	v_fma_f32 v19, v34, s43, -v18
	v_rndne_f32_e32 v20, v18
	v_fmac_f32_e32 v19, 0xb2a5705f, v34
	v_sub_f32_e32 v18, v18, v20
	v_add_f32_e32 v18, v18, v19
	v_exp_f32_e32 v18, v18
	v_cvt_i32_f32_e32 v19, v20
	v_ldexp_f32 v18, v18, v19
	v_mul_f32_e32 v19, 0xbfb8aa3b, v35
	v_fma_f32 v20, v35, s43, -v19
	v_rndne_f32_e32 v21, v19
	v_fmac_f32_e32 v20, 0xb2a5705f, v35
	v_sub_f32_e32 v19, v19, v21
	v_add_f32_e32 v19, v19, v20
	v_exp_f32_e32 v19, v19
	v_cvt_i32_f32_e32 v20, v21
	v_cndmask_b32_e32 v18, 0, v18, vcc
	v_cmp_ngt_f32_e32 vcc, s35, v34
	v_ldexp_f32 v19, v19, v20
	s_nop 0
	v_cndmask_b32_e32 v18, v179, v18, vcc
	v_cmp_nlt_f32_e32 vcc, s34, v35
	v_pk_fma_f32 v[20:21], v[30:31], v[126:127], v[38:39] op_sel_hi:[1,0,1]
	s_nop 0
	v_cndmask_b32_e32 v19, 0, v19, vcc
	v_cmp_ngt_f32_e32 vcc, s35, v35
	s_nop 1
	v_cndmask_b32_e32 v19, v179, v19, vcc
	v_pk_add_f32 v[18:19], v[18:19], 1.0 op_sel_hi:[1,0]
	s_nop 0
	v_div_scale_f32 v22, s[2:3], v19, v19, v35
	v_rcp_f32_e32 v23, v22
	s_nop 0
	v_fma_f32 v24, -v22, v23, 1.0
	v_fmac_f32_e32 v23, v24, v23
	v_div_scale_f32 v24, vcc, v35, v19, v35
	v_mul_f32_e32 v25, v24, v23
	v_fma_f32 v26, -v22, v25, v24
	v_fmac_f32_e32 v25, v26, v23
	v_fma_f32 v22, -v22, v25, v24
	v_div_fmas_f32 v22, v22, v23, v25
	v_div_fixup_f32 v19, v22, v19, v35
	v_div_scale_f32 v22, s[2:3], v18, v18, v34
	v_rcp_f32_e32 v23, v22
	s_nop 0
	v_fma_f32 v24, -v22, v23, 1.0
	v_fmac_f32_e32 v23, v24, v23
	v_div_scale_f32 v24, vcc, v34, v18, v34
	v_mul_f32_e32 v25, v24, v23
	v_fma_f32 v26, -v22, v25, v24
	v_fmac_f32_e32 v25, v26, v23
	v_fma_f32 v22, -v22, v25, v24
	v_div_fmas_f32 v22, v22, v23, v25
	v_div_fixup_f32 v18, v22, v18, v34
	v_pk_mul_f32 v[124:125], v[20:21], v[18:19]
	s_nop 0
	v_pk_fma_f32 v[16:17], v[124:125], v[124:125], v[16:17]
	v_mul_f32_e32 v18, v125, v125
	v_pk_add_f32 v[128:129], v[18:19], v[16:17] op_sel_hi:[0,1]
	global_load_dwordx4 v[36:39], v[130:131], off offset:128
	global_load_dwordx4 v[32:35], v[132:133], off offset:128
	global_load_dwordx4 v[28:31], v[130:131], off offset:160
	global_load_dwordx4 v[24:27], v[132:133], off offset:160
	global_load_dwordx4 v[20:23], v[130:131], off offset:192
	global_load_dwordx4 v[16:19], v[132:133], off offset:192
	global_load_dwordx4 v[44:47], v[130:131], off offset:224
	global_load_dwordx4 v[40:43], v[132:133], off offset:224
	s_waitcnt vmcnt(7)
	v_pk_fma_f32 v[0:1], v[0:1], v[126:127], v[36:37] op_sel_hi:[1,0,1]
	s_waitcnt vmcnt(6)
	v_mul_f32_e32 v103, 0xbfb8aa3b, v32
	v_fma_f32 v105, v32, s43, -v103
	v_rndne_f32_e32 v107, v103
	v_fmac_f32_e32 v105, 0xb2a5705f, v32
	v_sub_f32_e32 v103, v103, v107
	v_add_f32_e32 v103, v103, v105
	v_exp_f32_e32 v103, v103
	v_cvt_i32_f32_e32 v105, v107
	v_cmp_nlt_f32_e32 vcc, s34, v32
	v_ldexp_f32 v103, v103, v105
	s_nop 0
	v_cndmask_b32_e32 v103, 0, v103, vcc
	v_cmp_ngt_f32_e32 vcc, s35, v32
	s_nop 1
	v_cndmask_b32_e32 v130, v179, v103, vcc
	v_mul_f32_e32 v103, 0xbfb8aa3b, v33
	v_fma_f32 v105, v33, s43, -v103
	v_rndne_f32_e32 v107, v103
	v_fmac_f32_e32 v105, 0xb2a5705f, v33
	v_sub_f32_e32 v103, v103, v107
	v_add_f32_e32 v103, v103, v105
	v_exp_f32_e32 v103, v103
	v_cvt_i32_f32_e32 v105, v107
	v_cmp_nlt_f32_e32 vcc, s34, v33
	v_ldexp_f32 v103, v103, v105
	s_nop 0
	v_cndmask_b32_e32 v103, 0, v103, vcc
	v_cmp_ngt_f32_e32 vcc, s35, v33
	s_nop 1
	v_cndmask_b32_e32 v131, v179, v103, vcc
	v_pk_add_f32 v[36:37], v[130:131], 1.0 op_sel_hi:[1,0]
	s_nop 0
	v_div_scale_f32 v103, s[2:3], v37, v37, v33
	v_rcp_f32_e32 v105, v103
	s_nop 0
	v_fma_f32 v107, -v103, v105, 1.0
	v_fmac_f32_e32 v105, v107, v105
	v_div_scale_f32 v107, vcc, v33, v37, v33
	v_mul_f32_e32 v109, v107, v105
	v_fma_f32 v127, -v103, v109, v107
	v_fmac_f32_e32 v109, v127, v105
	v_fma_f32 v103, -v103, v109, v107
	v_div_fmas_f32 v103, v103, v105, v109
	v_div_fixup_f32 v33, v103, v37, v33
	v_div_scale_f32 v37, s[2:3], v36, v36, v32
	v_rcp_f32_e32 v103, v37
	v_pk_fma_f32 v[2:3], v[2:3], v[126:127], v[38:39] op_sel_hi:[1,0,1]
	s_waitcnt vmcnt(5)
	v_pk_fma_f32 v[4:5], v[4:5], v[126:127], v[28:29] op_sel_hi:[1,0,1]
	v_pk_fma_f32 v[6:7], v[6:7], v[126:127], v[30:31] op_sel_hi:[1,0,1]
	v_fma_f32 v105, -v37, v103, 1.0
	v_fmac_f32_e32 v103, v105, v103
	v_div_scale_f32 v105, vcc, v32, v36, v32
	v_mul_f32_e32 v107, v105, v103
	v_fma_f32 v109, -v37, v107, v105
	v_fmac_f32_e32 v107, v109, v103
	v_fma_f32 v37, -v37, v107, v105
	v_div_fmas_f32 v37, v37, v103, v107
	v_div_fixup_f32 v32, v37, v36, v32
	v_pk_mul_f32 v[0:1], v[0:1], v[32:33]
	v_cmp_nlt_f32_e32 vcc, s34, v34
	v_pk_fma_f32 v[32:33], v[0:1], v[0:1], v[128:129]
	v_mul_f32_e32 v36, v1, v1
	v_pk_add_f32 v[32:33], v[36:37], v[32:33] op_sel_hi:[0,1]
	v_mul_f32_e32 v36, 0xbfb8aa3b, v34
	v_fma_f32 v37, v34, s43, -v36
	v_rndne_f32_e32 v103, v36
	v_fmac_f32_e32 v37, 0xb2a5705f, v34
	v_sub_f32_e32 v36, v36, v103
	v_add_f32_e32 v36, v36, v37
	v_exp_f32_e32 v36, v36
	v_cvt_i32_f32_e32 v37, v103
	s_waitcnt vmcnt(3)
	v_pk_fma_f32 v[8:9], v[8:9], v[126:127], v[20:21] op_sel_hi:[1,0,1]
	v_pk_fma_f32 v[10:11], v[10:11], v[126:127], v[22:23] op_sel_hi:[1,0,1]
	s_waitcnt vmcnt(1)
	v_pk_fma_f32 v[12:13], v[12:13], v[126:127], v[44:45] op_sel_hi:[1,0,1]
	v_ldexp_f32 v36, v36, v37
	v_mul_f32_e32 v37, 0xbfb8aa3b, v35
	v_fma_f32 v103, v35, s43, -v37
	v_rndne_f32_e32 v105, v37
	v_fmac_f32_e32 v103, 0xb2a5705f, v35
	v_sub_f32_e32 v37, v37, v105
	v_add_f32_e32 v37, v37, v103
	v_exp_f32_e32 v37, v37
	v_cvt_i32_f32_e32 v103, v105
	v_cndmask_b32_e32 v36, 0, v36, vcc
	v_cmp_ngt_f32_e32 vcc, s35, v34
	v_pk_fma_f32 v[14:15], v[14:15], v[126:127], v[46:47] op_sel_hi:[1,0,1]
	v_ldexp_f32 v37, v37, v103
	v_cndmask_b32_e32 v36, v179, v36, vcc
	v_cmp_nlt_f32_e32 vcc, s34, v35
	s_nop 1
	v_cndmask_b32_e32 v37, 0, v37, vcc
	v_cmp_ngt_f32_e32 vcc, s35, v35
	s_nop 1
	v_cndmask_b32_e32 v37, v179, v37, vcc
	v_pk_add_f32 v[36:37], v[36:37], 1.0 op_sel_hi:[1,0]
	s_nop 0
	v_div_scale_f32 v38, s[2:3], v37, v37, v35
	v_rcp_f32_e32 v39, v38
	s_nop 0
	v_fma_f32 v103, -v38, v39, 1.0
	v_fmac_f32_e32 v39, v103, v39
	v_div_scale_f32 v103, vcc, v35, v37, v35
	v_mul_f32_e32 v105, v103, v39
	v_fma_f32 v107, -v38, v105, v103
	v_fmac_f32_e32 v105, v107, v39
	v_fma_f32 v38, -v38, v105, v103
	v_div_fmas_f32 v38, v38, v39, v105
	v_div_fixup_f32 v35, v38, v37, v35
	v_div_scale_f32 v37, s[2:3], v36, v36, v34
	v_rcp_f32_e32 v38, v37
	s_nop 0
	v_fma_f32 v39, -v37, v38, 1.0
	v_fmac_f32_e32 v38, v39, v38
	v_div_scale_f32 v39, vcc, v34, v36, v34
	v_mul_f32_e32 v103, v39, v38
	v_fma_f32 v105, -v37, v103, v39
	v_fmac_f32_e32 v103, v105, v38
	v_fma_f32 v37, -v37, v103, v39
	v_div_fmas_f32 v37, v37, v38, v103
	v_div_fixup_f32 v34, v37, v36, v34
	v_pk_mul_f32 v[2:3], v[2:3], v[34:35]
	v_cmp_nlt_f32_e32 vcc, s34, v24
	v_pk_fma_f32 v[32:33], v[2:3], v[2:3], v[32:33]
	v_mul_f32_e32 v34, v3, v3
	v_pk_add_f32 v[32:33], v[34:35], v[32:33] op_sel_hi:[0,1]
	v_mul_f32_e32 v34, 0xbfb8aa3b, v24
	v_fma_f32 v35, v24, s43, -v34
	v_rndne_f32_e32 v36, v34
	v_fmac_f32_e32 v35, 0xb2a5705f, v24
	v_sub_f32_e32 v34, v34, v36
	v_add_f32_e32 v34, v34, v35
	v_exp_f32_e32 v34, v34
	v_cvt_i32_f32_e32 v35, v36
	v_ldexp_f32 v34, v34, v35
	v_mul_f32_e32 v35, 0xbfb8aa3b, v25
	v_fma_f32 v36, v25, s43, -v35
	v_rndne_f32_e32 v37, v35
	v_fmac_f32_e32 v36, 0xb2a5705f, v25
	v_sub_f32_e32 v35, v35, v37
	v_add_f32_e32 v35, v35, v36
	v_exp_f32_e32 v35, v35
	v_cvt_i32_f32_e32 v36, v37
	v_cndmask_b32_e32 v34, 0, v34, vcc
	v_cmp_ngt_f32_e32 vcc, s35, v24
	v_ldexp_f32 v35, v35, v36
	s_nop 0
	v_cndmask_b32_e32 v34, v179, v34, vcc
	v_cmp_nlt_f32_e32 vcc, s34, v25
	s_nop 1
	v_cndmask_b32_e32 v35, 0, v35, vcc
	v_cmp_ngt_f32_e32 vcc, s35, v25
	s_nop 1
	v_cndmask_b32_e32 v35, v179, v35, vcc
	v_pk_add_f32 v[28:29], v[34:35], 1.0 op_sel_hi:[1,0]
	s_nop 0
	v_div_scale_f32 v34, s[2:3], v29, v29, v25
	v_rcp_f32_e32 v35, v34
	s_nop 0
	v_fma_f32 v36, -v34, v35, 1.0
	v_fmac_f32_e32 v35, v36, v35
	v_div_scale_f32 v36, vcc, v25, v29, v25
	v_mul_f32_e32 v37, v36, v35
	v_fma_f32 v38, -v34, v37, v36
	v_fmac_f32_e32 v37, v38, v35
	v_fma_f32 v34, -v34, v37, v36
	v_div_fmas_f32 v34, v34, v35, v37
	v_div_fixup_f32 v25, v34, v29, v25
	v_div_scale_f32 v29, s[2:3], v28, v28, v24
	v_rcp_f32_e32 v34, v29
	s_nop 0
	v_fma_f32 v35, -v29, v34, 1.0
	v_fmac_f32_e32 v34, v35, v34
	v_div_scale_f32 v35, vcc, v24, v28, v24
	v_mul_f32_e32 v36, v35, v34
	v_fma_f32 v37, -v29, v36, v35
	v_fmac_f32_e32 v36, v37, v34
	v_fma_f32 v29, -v29, v36, v35
	v_div_fmas_f32 v29, v29, v34, v36
	v_div_fixup_f32 v24, v29, v28, v24
	v_pk_mul_f32 v[4:5], v[4:5], v[24:25]
	v_cmp_nlt_f32_e32 vcc, s34, v26
	v_pk_fma_f32 v[24:25], v[4:5], v[4:5], v[32:33]
	v_mul_f32_e32 v28, v5, v5
	v_pk_add_f32 v[24:25], v[28:29], v[24:25] op_sel_hi:[0,1]
	v_mul_f32_e32 v28, 0xbfb8aa3b, v26
	v_fma_f32 v29, v26, s43, -v28
	v_rndne_f32_e32 v32, v28
	v_fmac_f32_e32 v29, 0xb2a5705f, v26
	v_sub_f32_e32 v28, v28, v32
	v_add_f32_e32 v28, v28, v29
	v_exp_f32_e32 v28, v28
	v_cvt_i32_f32_e32 v29, v32
	v_ldexp_f32 v28, v28, v29
	v_mul_f32_e32 v29, 0xbfb8aa3b, v27
	v_fma_f32 v32, v27, s43, -v29
	v_rndne_f32_e32 v33, v29
	v_fmac_f32_e32 v32, 0xb2a5705f, v27
	v_sub_f32_e32 v29, v29, v33
	v_add_f32_e32 v29, v29, v32
	v_exp_f32_e32 v29, v29
	v_cvt_i32_f32_e32 v32, v33
	v_cndmask_b32_e32 v28, 0, v28, vcc
	v_cmp_ngt_f32_e32 vcc, s35, v26
	v_ldexp_f32 v29, v29, v32
	s_nop 0
	v_cndmask_b32_e32 v28, v179, v28, vcc
	v_cmp_nlt_f32_e32 vcc, s34, v27
	s_nop 1
	v_cndmask_b32_e32 v29, 0, v29, vcc
	v_cmp_ngt_f32_e32 vcc, s35, v27
	s_nop 1
	v_cndmask_b32_e32 v29, v179, v29, vcc
	v_pk_add_f32 v[28:29], v[28:29], 1.0 op_sel_hi:[1,0]
	s_nop 0
	v_div_scale_f32 v30, s[2:3], v29, v29, v27
	v_rcp_f32_e32 v31, v30
	s_nop 0
	v_fma_f32 v32, -v30, v31, 1.0
	v_fmac_f32_e32 v31, v32, v31
	v_div_scale_f32 v32, vcc, v27, v29, v27
	v_mul_f32_e32 v33, v32, v31
	v_fma_f32 v34, -v30, v33, v32
	v_fmac_f32_e32 v33, v34, v31
	v_fma_f32 v30, -v30, v33, v32
	v_div_fmas_f32 v30, v30, v31, v33
	v_div_fixup_f32 v27, v30, v29, v27
	v_div_scale_f32 v29, s[2:3], v28, v28, v26
	v_rcp_f32_e32 v30, v29
	s_nop 0
	v_fma_f32 v31, -v29, v30, 1.0
	v_fmac_f32_e32 v30, v31, v30
	v_div_scale_f32 v31, vcc, v26, v28, v26
	v_mul_f32_e32 v32, v31, v30
	v_fma_f32 v33, -v29, v32, v31
	v_fmac_f32_e32 v32, v33, v30
	v_fma_f32 v29, -v29, v32, v31
	v_div_fmas_f32 v29, v29, v30, v32
	v_div_fixup_f32 v26, v29, v28, v26
	v_pk_mul_f32 v[6:7], v[6:7], v[26:27]
	v_cmp_nlt_f32_e32 vcc, s34, v16
	v_pk_fma_f32 v[24:25], v[6:7], v[6:7], v[24:25]
	v_mul_f32_e32 v26, v7, v7
	v_pk_add_f32 v[24:25], v[26:27], v[24:25] op_sel_hi:[0,1]
	v_mul_f32_e32 v26, 0xbfb8aa3b, v16
	v_fma_f32 v27, v16, s43, -v26
	v_rndne_f32_e32 v28, v26
	v_fmac_f32_e32 v27, 0xb2a5705f, v16
	v_sub_f32_e32 v26, v26, v28
	v_add_f32_e32 v26, v26, v27
	v_exp_f32_e32 v26, v26
	v_cvt_i32_f32_e32 v27, v28
	v_ldexp_f32 v26, v26, v27
	v_mul_f32_e32 v27, 0xbfb8aa3b, v17
	v_fma_f32 v28, v17, s43, -v27
	v_rndne_f32_e32 v29, v27
	v_fmac_f32_e32 v28, 0xb2a5705f, v17
	v_sub_f32_e32 v27, v27, v29
	v_add_f32_e32 v27, v27, v28
	v_exp_f32_e32 v27, v27
	v_cvt_i32_f32_e32 v28, v29
	v_cndmask_b32_e32 v26, 0, v26, vcc
	v_cmp_ngt_f32_e32 vcc, s35, v16
	v_ldexp_f32 v27, v27, v28
	s_nop 0
	v_cndmask_b32_e32 v26, v179, v26, vcc
	v_cmp_nlt_f32_e32 vcc, s34, v17
	s_nop 1
	v_cndmask_b32_e32 v27, 0, v27, vcc
	v_cmp_ngt_f32_e32 vcc, s35, v17
	s_nop 1
	v_cndmask_b32_e32 v27, v179, v27, vcc
	v_pk_add_f32 v[20:21], v[26:27], 1.0 op_sel_hi:[1,0]
	s_nop 0
	v_div_scale_f32 v26, s[2:3], v21, v21, v17
	v_rcp_f32_e32 v27, v26
	s_nop 0
	v_fma_f32 v28, -v26, v27, 1.0
	v_fmac_f32_e32 v27, v28, v27
	v_div_scale_f32 v28, vcc, v17, v21, v17
	v_mul_f32_e32 v29, v28, v27
	v_fma_f32 v30, -v26, v29, v28
	v_fmac_f32_e32 v29, v30, v27
	v_fma_f32 v26, -v26, v29, v28
	v_div_fmas_f32 v26, v26, v27, v29
	v_div_fixup_f32 v17, v26, v21, v17
	v_div_scale_f32 v21, s[2:3], v20, v20, v16
	v_rcp_f32_e32 v26, v21
	s_nop 0
	v_fma_f32 v27, -v21, v26, 1.0
	v_fmac_f32_e32 v26, v27, v26
	v_div_scale_f32 v27, vcc, v16, v20, v16
	v_mul_f32_e32 v28, v27, v26
	v_fma_f32 v29, -v21, v28, v27
	v_fmac_f32_e32 v28, v29, v26
	v_fma_f32 v21, -v21, v28, v27
	v_div_fmas_f32 v21, v21, v26, v28
	v_div_fixup_f32 v16, v21, v20, v16
	v_pk_mul_f32 v[8:9], v[8:9], v[16:17]
	v_cmp_nlt_f32_e32 vcc, s34, v18
	v_pk_fma_f32 v[16:17], v[8:9], v[8:9], v[24:25]
	v_mul_f32_e32 v20, v9, v9
	v_pk_add_f32 v[16:17], v[20:21], v[16:17] op_sel_hi:[0,1]
	v_mul_f32_e32 v20, 0xbfb8aa3b, v18
	v_fma_f32 v21, v18, s43, -v20
	v_rndne_f32_e32 v24, v20
	v_fmac_f32_e32 v21, 0xb2a5705f, v18
	v_sub_f32_e32 v20, v20, v24
	v_add_f32_e32 v20, v20, v21
	v_exp_f32_e32 v20, v20
	v_cvt_i32_f32_e32 v21, v24
	v_ldexp_f32 v20, v20, v21
	v_mul_f32_e32 v21, 0xbfb8aa3b, v19
	v_fma_f32 v24, v19, s43, -v21
	v_rndne_f32_e32 v25, v21
	v_fmac_f32_e32 v24, 0xb2a5705f, v19
	v_sub_f32_e32 v21, v21, v25
	v_add_f32_e32 v21, v21, v24
	v_exp_f32_e32 v21, v21
	v_cvt_i32_f32_e32 v24, v25
	v_cndmask_b32_e32 v20, 0, v20, vcc
	v_cmp_ngt_f32_e32 vcc, s35, v18
	v_ldexp_f32 v21, v21, v24
	s_nop 0
	v_cndmask_b32_e32 v20, v179, v20, vcc
	v_cmp_nlt_f32_e32 vcc, s34, v19
	s_nop 1
	v_cndmask_b32_e32 v21, 0, v21, vcc
	v_cmp_ngt_f32_e32 vcc, s35, v19
	s_nop 1
	v_cndmask_b32_e32 v21, v179, v21, vcc
	v_pk_add_f32 v[20:21], v[20:21], 1.0 op_sel_hi:[1,0]
	s_nop 0
	v_div_scale_f32 v22, s[2:3], v21, v21, v19
	v_rcp_f32_e32 v23, v22
	s_nop 0
	v_fma_f32 v24, -v22, v23, 1.0
	v_fmac_f32_e32 v23, v24, v23
	v_div_scale_f32 v24, vcc, v19, v21, v19
	v_mul_f32_e32 v25, v24, v23
	v_fma_f32 v26, -v22, v25, v24
	v_fmac_f32_e32 v25, v26, v23
	v_fma_f32 v22, -v22, v25, v24
	v_div_fmas_f32 v22, v22, v23, v25
	v_div_fixup_f32 v19, v22, v21, v19
	v_div_scale_f32 v21, s[2:3], v20, v20, v18
	v_rcp_f32_e32 v22, v21
	s_nop 0
	v_fma_f32 v23, -v21, v22, 1.0
	v_fmac_f32_e32 v22, v23, v22
	v_div_scale_f32 v23, vcc, v18, v20, v18
	v_mul_f32_e32 v24, v23, v22
	v_fma_f32 v25, -v21, v24, v23
	v_fmac_f32_e32 v24, v25, v22
	v_fma_f32 v21, -v21, v24, v23
	v_div_fmas_f32 v21, v21, v22, v24
	v_div_fixup_f32 v18, v21, v20, v18
	v_pk_mul_f32 v[10:11], v[10:11], v[18:19]
	s_waitcnt vmcnt(0)
	v_cmp_nlt_f32_e32 vcc, s34, v40
	v_pk_fma_f32 v[16:17], v[10:11], v[10:11], v[16:17]
	v_mul_f32_e32 v18, v11, v11
	v_pk_add_f32 v[16:17], v[18:19], v[16:17] op_sel_hi:[0,1]
	v_mul_f32_e32 v18, 0xbfb8aa3b, v40
	v_fma_f32 v19, v40, s43, -v18
	v_rndne_f32_e32 v20, v18
	v_fmac_f32_e32 v19, 0xb2a5705f, v40
	v_sub_f32_e32 v18, v18, v20
	v_add_f32_e32 v18, v18, v19
	v_exp_f32_e32 v18, v18
	v_cvt_i32_f32_e32 v19, v20
	v_ldexp_f32 v18, v18, v19
	v_mul_f32_e32 v19, 0xbfb8aa3b, v41
	v_fma_f32 v20, v41, s43, -v19
	v_rndne_f32_e32 v21, v19
	v_fmac_f32_e32 v20, 0xb2a5705f, v41
	v_sub_f32_e32 v19, v19, v21
	v_add_f32_e32 v19, v19, v20
	v_exp_f32_e32 v19, v19
	v_cvt_i32_f32_e32 v20, v21
	v_cndmask_b32_e32 v18, 0, v18, vcc
	v_cmp_ngt_f32_e32 vcc, s35, v40
	v_ldexp_f32 v19, v19, v20
	s_nop 0
	v_cndmask_b32_e32 v18, v179, v18, vcc
	v_cmp_nlt_f32_e32 vcc, s34, v41
	s_nop 1
	v_cndmask_b32_e32 v19, 0, v19, vcc
	v_cmp_ngt_f32_e32 vcc, s35, v41
	s_nop 1
	v_cndmask_b32_e32 v19, v179, v19, vcc
	v_pk_add_f32 v[18:19], v[18:19], 1.0 op_sel_hi:[1,0]
	s_nop 0
	v_div_scale_f32 v20, s[2:3], v19, v19, v41
	v_rcp_f32_e32 v21, v20
	s_nop 0
	v_fma_f32 v22, -v20, v21, 1.0
	v_fmac_f32_e32 v21, v22, v21
	v_div_scale_f32 v22, vcc, v41, v19, v41
	v_mul_f32_e32 v23, v22, v21
	v_fma_f32 v24, -v20, v23, v22
	v_fmac_f32_e32 v23, v24, v21
	v_fma_f32 v20, -v20, v23, v22
	v_div_fmas_f32 v20, v20, v21, v23
	v_div_fixup_f32 v19, v20, v19, v41
	v_div_scale_f32 v20, s[2:3], v18, v18, v40
	v_rcp_f32_e32 v21, v20
	s_nop 0
	v_fma_f32 v22, -v20, v21, 1.0
	v_fmac_f32_e32 v21, v22, v21
	v_div_scale_f32 v22, vcc, v40, v18, v40
	v_mul_f32_e32 v23, v22, v21
	v_fma_f32 v24, -v20, v23, v22
	v_fmac_f32_e32 v23, v24, v21
	v_fma_f32 v20, -v20, v23, v22
	v_div_fmas_f32 v20, v20, v21, v23
	v_div_fixup_f32 v18, v20, v18, v40
	v_pk_mul_f32 v[12:13], v[12:13], v[18:19]
	v_cmp_nlt_f32_e32 vcc, s34, v42
	v_pk_fma_f32 v[16:17], v[12:13], v[12:13], v[16:17]
	v_mul_f32_e32 v18, v13, v13
	v_pk_add_f32 v[16:17], v[18:19], v[16:17] op_sel_hi:[0,1]
	v_mul_f32_e32 v18, 0xbfb8aa3b, v42
	v_fma_f32 v19, v42, s43, -v18
	v_rndne_f32_e32 v20, v18
	v_fmac_f32_e32 v19, 0xb2a5705f, v42
	v_sub_f32_e32 v18, v18, v20
	v_add_f32_e32 v18, v18, v19
	v_exp_f32_e32 v18, v18
	v_cvt_i32_f32_e32 v19, v20
	v_ldexp_f32 v18, v18, v19
	v_mul_f32_e32 v19, 0xbfb8aa3b, v43
	v_fma_f32 v20, v43, s43, -v19
	v_rndne_f32_e32 v21, v19
	v_fmac_f32_e32 v20, 0xb2a5705f, v43
	v_sub_f32_e32 v19, v19, v21
	v_add_f32_e32 v19, v19, v20
	v_exp_f32_e32 v19, v19
	v_cvt_i32_f32_e32 v20, v21
	v_cndmask_b32_e32 v18, 0, v18, vcc
	v_cmp_ngt_f32_e32 vcc, s35, v42
	v_ldexp_f32 v19, v19, v20
	s_nop 0
	v_cndmask_b32_e32 v18, v179, v18, vcc
	v_cmp_nlt_f32_e32 vcc, s34, v43
	s_nop 1
	v_cndmask_b32_e32 v19, 0, v19, vcc
	v_cmp_ngt_f32_e32 vcc, s35, v43
	s_nop 1
	v_cndmask_b32_e32 v19, v179, v19, vcc
	v_pk_add_f32 v[18:19], v[18:19], 1.0 op_sel_hi:[1,0]
	s_nop 0
	v_div_scale_f32 v20, s[2:3], v19, v19, v43
	v_rcp_f32_e32 v21, v20
	s_nop 0
	v_fma_f32 v22, -v20, v21, 1.0
	v_fmac_f32_e32 v21, v22, v21
	v_div_scale_f32 v22, vcc, v43, v19, v43
	v_mul_f32_e32 v23, v22, v21
	v_fma_f32 v24, -v20, v23, v22
	v_fmac_f32_e32 v23, v24, v21
	v_fma_f32 v20, -v20, v23, v22
	v_div_fmas_f32 v20, v20, v21, v23
	v_div_fixup_f32 v19, v20, v19, v43
	v_div_scale_f32 v20, s[2:3], v18, v18, v42
	v_rcp_f32_e32 v21, v20
	s_nop 0
	v_fma_f32 v22, -v20, v21, 1.0
	v_fmac_f32_e32 v21, v22, v21
	v_div_scale_f32 v22, vcc, v42, v18, v42
	v_mul_f32_e32 v23, v22, v21
	v_fma_f32 v24, -v20, v23, v22
	v_fmac_f32_e32 v23, v24, v21
	v_fma_f32 v20, -v20, v23, v22
	v_div_fmas_f32 v20, v20, v21, v23
	v_div_fixup_f32 v18, v20, v18, v42
	v_pk_mul_f32 v[14:15], v[14:15], v[18:19]
	s_nop 0
	v_pk_fma_f32 v[16:17], v[14:15], v[14:15], v[16:17]
	v_mul_f32_e32 v18, v15, v15
	v_pk_add_f32 v[16:17], v[18:19], v[16:17] op_sel_hi:[0,1]
	v_mov_b32_e32 v17, v16
	s_nop 1
	v_permlane32_swap_b32_e32 v16, v17
	s_and_saveexec_b64 s[4:5], s[48:49]
	s_cbranch_execz .LBB0_1284
	v_add_f32_e32 v16, v16, v17
	ds_write_b32 v97, v16 offset:1024
	s_branch .LBB0_1284
